# speedup vs baseline: 1.0649x; 1.0649x over previous
; DI unsigned pack2(float a, float b) { f32x2_t v = {a, b}; return __builtin_bit_cast(unsigned, __builtin_convertvector(v, bf16x2_t)); }
; DI float bflo(unsigned p) { return __uint_as_float(p << 16); }
; DI float bfhi(unsigned p) { return __uint_as_float(p & 0xffff0000u); }
; DI void hgrn_scan(const Params& P, int half, int vb, int nb) {
;   const int nch = half ? 256 : 32;
;   const int nseq = half ? 1 : 8;
;   const int total = nseq * 131072;
;   for (int idx = vb * 512 + threadIdx.x; idx < total; idx += nb * 512) {
;     const int dk2 = idx & 63, dv = (idx >> 6) & 127, dir = (idx >> 13) & 1, head = (idx >> 14) & 7, seq = idx >> 17;
;     float s0 = 0.f, s1 = 0.f;
;     _Pragma("unroll 8") for (int step = 0; step < nch; ++step) {
;       const int c = seq * nch + (dir ? (nch - 1 - step) : step);
;       const size_t base = ((size_t)c * 8 + head) * 2 + dir;
;       unsigned* p = (unsigned*)(P.st + base * 16384 + dv * 128 + dk2 * 2);
;       const unsigned u = *p;
;       const float2 d = *(const float2*)(P.dt + base * 128 + dk2 * 2);
;       *p = pack2(s0, s1);
;       s0 = d.x * s0 + bflo(u); s1 = d.y * s1 + bfhi(u);
;     }
;   }
.LBB0_605:
	v_lshlrev_b32_e32 v4, 1, v1
	v_lshlrev_b32_e32 v2, 2, v1
	v_and_b32_e32 v152, 0x7f00, v2
	v_and_b32_e32 v4, 0x7e, v4
	v_ashrrev_i32_e32 v0, 17, v1
	v_lshl_add_u64 v[2:3], s[24:25], 0, v[152:153]
	v_lshlrev_b32_e32 v152, 1, v4
	v_lshlrev_b32_e32 v30, s8, v0
	v_and_b32_e32 v0, 0x2000, v1
	v_lshl_add_u64 v[2:3], v[2:3], 0, v[152:153]
	v_lshlrev_b32_e32 v152, 2, v4
	v_mov_b32_e32 v6, 0
	s_mov_b32 s10, 0
	v_cmp_eq_u32_e32 vcc, 0, v0
	v_bfe_u32 v0, v1, 13, 4
	v_lshl_add_u64 v[4:5], s[26:27], 0, v[152:153]
	s_mov_b32 s11, s9
	v_mov_b32_e32 v7, v6
	v_mov_b32_e32 v8, s11
	v_cndmask_b32_e64 v8, v8, 0, vcc
	v_add_u32_e32 v8, v8, v30
	v_lshl_or_b32 v8, v8, 4, v0
	v_mov_b32_e32 v9, 0
	v_lshlrev_b64 v[10:11], 15, v[8:9]
	v_lshlrev_b64 v[8:9], 9, v[8:9]
	v_lshl_add_u64 v[2:3], v[2:3], 0, v[10:11]
	v_lshl_add_u64 v[4:5], v[4:5], 0, v[8:9]
	v_mov_b32_e32 v0, 0xfff80000
	v_mov_b32_e32 v12, 0x80000
	v_cndmask_b32_e32 v8, v0, v12, vcc
	v_mov_b32_e32 v0, 0xffffe000
	v_mov_b32_e32 v12, 0x2000
	v_cndmask_b32_e32 v10, v0, v12, vcc
	v_cndmask_b32_e64 v9, -1, 0, vcc
	v_mov_b32_e32 v11, v9
	v_mov_b32_e32 v12, v2
	v_mov_b32_e32 v13, v3
	global_load_dword v14, v[2:3], off
	global_load_dwordx2 v[22:23], v[4:5], off
	v_lshl_add_u64 v[2:3], v[2:3], 0, v[8:9]
	v_lshl_add_u64 v[4:5], v[4:5], 0, v[10:11]
	global_load_dword v15, v[2:3], off
	global_load_dwordx2 v[24:25], v[4:5], off
	v_lshl_add_u64 v[2:3], v[2:3], 0, v[8:9]
	v_lshl_add_u64 v[4:5], v[4:5], 0, v[10:11]
	global_load_dword v16, v[2:3], off
	global_load_dwordx2 v[26:27], v[4:5], off
	v_lshl_add_u64 v[2:3], v[2:3], 0, v[8:9]
	v_lshl_add_u64 v[4:5], v[4:5], 0, v[10:11]
	global_load_dword v17, v[2:3], off
	global_load_dwordx2 v[28:29], v[4:5], off
	v_lshl_add_u64 v[2:3], v[2:3], 0, v[8:9]
	v_lshl_add_u64 v[4:5], v[4:5], 0, v[10:11]
	global_load_dword v18, v[2:3], off
	global_load_dwordx2 v[30:31], v[4:5], off
	v_lshl_add_u64 v[2:3], v[2:3], 0, v[8:9]
	v_lshl_add_u64 v[4:5], v[4:5], 0, v[10:11]
	global_load_dword v19, v[2:3], off
	global_load_dwordx2 v[32:33], v[4:5], off
	v_lshl_add_u64 v[2:3], v[2:3], 0, v[8:9]
	v_lshl_add_u64 v[4:5], v[4:5], 0, v[10:11]
	global_load_dword v20, v[2:3], off
	global_load_dwordx2 v[34:35], v[4:5], off
	v_lshl_add_u64 v[2:3], v[2:3], 0, v[8:9]
	v_lshl_add_u64 v[4:5], v[4:5], 0, v[10:11]
	global_load_dword v21, v[2:3], off
	global_load_dwordx2 v[214:215], v[4:5], off
	v_lshl_add_u64 v[2:3], v[2:3], 0, v[8:9]
	v_lshl_add_u64 v[4:5], v[4:5], 0, v[10:11]
.Lscan_loop:
	global_load_dword v216, v[2:3], off
	global_load_dwordx2 v[224:225], v[4:5], off
	v_lshl_add_u64 v[2:3], v[2:3], 0, v[8:9]
	v_lshl_add_u64 v[4:5], v[4:5], 0, v[10:11]
	global_load_dword v217, v[2:3], off
	global_load_dwordx2 v[226:227], v[4:5], off
	v_lshl_add_u64 v[2:3], v[2:3], 0, v[8:9]
	v_lshl_add_u64 v[4:5], v[4:5], 0, v[10:11]
	global_load_dword v218, v[2:3], off
	global_load_dwordx2 v[228:229], v[4:5], off
	v_lshl_add_u64 v[2:3], v[2:3], 0, v[8:9]
	v_lshl_add_u64 v[4:5], v[4:5], 0, v[10:11]
	global_load_dword v219, v[2:3], off
	global_load_dwordx2 v[230:231], v[4:5], off
	v_lshl_add_u64 v[2:3], v[2:3], 0, v[8:9]
	v_lshl_add_u64 v[4:5], v[4:5], 0, v[10:11]
	global_load_dword v220, v[2:3], off
	global_load_dwordx2 v[232:233], v[4:5], off
	v_lshl_add_u64 v[2:3], v[2:3], 0, v[8:9]
	v_lshl_add_u64 v[4:5], v[4:5], 0, v[10:11]
	global_load_dword v221, v[2:3], off
	global_load_dwordx2 v[234:235], v[4:5], off
	v_lshl_add_u64 v[2:3], v[2:3], 0, v[8:9]
	v_lshl_add_u64 v[4:5], v[4:5], 0, v[10:11]
	global_load_dword v222, v[2:3], off
	global_load_dwordx2 v[252:253], v[4:5], off
	v_lshl_add_u64 v[2:3], v[2:3], 0, v[8:9]
	v_lshl_add_u64 v[4:5], v[4:5], 0, v[10:11]
	global_load_dword v223, v[2:3], off
	global_load_dwordx2 v[254:255], v[4:5], off
	v_lshl_add_u64 v[2:3], v[2:3], 0, v[8:9]
	v_lshl_add_u64 v[4:5], v[4:5], 0, v[10:11]
	v_cvt_pk_bf16_f32 v213, v6, v7
	global_store_dword v[12:13], v213, off
	v_lshl_add_u64 v[12:13], v[12:13], 0, v[8:9]
	s_waitcnt vmcnt(31)
	v_lshlrev_b32_e32 v0, 16, v14
	v_and_b32_e32 v14, 0xffff0000, v14
	v_fma_f32 v6, v6, v22, v0
	v_fma_f32 v7, v7, v23, v14
	v_cvt_pk_bf16_f32 v213, v6, v7
	global_store_dword v[12:13], v213, off
	v_lshl_add_u64 v[12:13], v[12:13], 0, v[8:9]
	s_waitcnt vmcnt(30)
	v_lshlrev_b32_e32 v0, 16, v15
	v_and_b32_e32 v15, 0xffff0000, v15
	v_fma_f32 v6, v6, v24, v0
	v_fma_f32 v7, v7, v25, v15
	v_cvt_pk_bf16_f32 v213, v6, v7
	global_store_dword v[12:13], v213, off
	v_lshl_add_u64 v[12:13], v[12:13], 0, v[8:9]
	s_waitcnt vmcnt(29)
	v_lshlrev_b32_e32 v0, 16, v16
	v_and_b32_e32 v16, 0xffff0000, v16
	v_fma_f32 v6, v6, v26, v0
	v_fma_f32 v7, v7, v27, v16
	v_cvt_pk_bf16_f32 v213, v6, v7
	global_store_dword v[12:13], v213, off
	v_lshl_add_u64 v[12:13], v[12:13], 0, v[8:9]
	s_waitcnt vmcnt(28)
	v_lshlrev_b32_e32 v0, 16, v17
	v_and_b32_e32 v17, 0xffff0000, v17
	v_fma_f32 v6, v6, v28, v0
	v_fma_f32 v7, v7, v29, v17
	v_cvt_pk_bf16_f32 v213, v6, v7
	global_store_dword v[12:13], v213, off
	v_lshl_add_u64 v[12:13], v[12:13], 0, v[8:9]
	s_waitcnt vmcnt(27)
	v_lshlrev_b32_e32 v0, 16, v18
	v_and_b32_e32 v18, 0xffff0000, v18
	v_fma_f32 v6, v6, v30, v0
	v_fma_f32 v7, v7, v31, v18
	v_cvt_pk_bf16_f32 v213, v6, v7
	global_store_dword v[12:13], v213, off
	v_lshl_add_u64 v[12:13], v[12:13], 0, v[8:9]
	s_waitcnt vmcnt(26)
	v_lshlrev_b32_e32 v0, 16, v19
	v_and_b32_e32 v19, 0xffff0000, v19
	v_fma_f32 v6, v6, v32, v0
	v_fma_f32 v7, v7, v33, v19
	v_cvt_pk_bf16_f32 v213, v6, v7
	global_store_dword v[12:13], v213, off
	v_lshl_add_u64 v[12:13], v[12:13], 0, v[8:9]
	s_waitcnt vmcnt(25)
	v_lshlrev_b32_e32 v0, 16, v20
	v_and_b32_e32 v20, 0xffff0000, v20
	v_fma_f32 v6, v6, v34, v0
	v_fma_f32 v7, v7, v35, v20
	v_cvt_pk_bf16_f32 v213, v6, v7
	global_store_dword v[12:13], v213, off
	v_lshl_add_u64 v[12:13], v[12:13], 0, v[8:9]
	s_waitcnt vmcnt(24)
	v_lshlrev_b32_e32 v0, 16, v21
	v_and_b32_e32 v21, 0xffff0000, v21
	v_fma_f32 v6, v6, v214, v0
	v_fma_f32 v7, v7, v215, v21
	s_add_i32 s10, s10, 16
	s_cmp_ge_u32 s10, s7
	s_cbranch_scc1 .Lscan_tail
; DI unsigned pack2(float a, float b) { f32x2_t v = {a, b}; return __builtin_bit_cast(unsigned, __builtin_convertvector(v, bf16x2_t)); }
; DI float bflo(unsigned p) { return __uint_as_float(p << 16); }
; DI float bfhi(unsigned p) { return __uint_as_float(p & 0xffff0000u); }
; DI void hgrn_scan(const Params& P, int half, int vb, int nb) {
;   const int nch = half ? 256 : 32;
;   const int nseq = half ? 1 : 8;
;   const int total = nseq * 131072;
;   for (int idx = vb * 512 + threadIdx.x; idx < total; idx += nb * 512) {
;     const int dk2 = idx & 63, dv = (idx >> 6) & 127, dir = (idx >> 13) & 1, head = (idx >> 14) & 7, seq = idx >> 17;
;     float s0 = 0.f, s1 = 0.f;
;     _Pragma("unroll 8") for (int step = 0; step < nch; ++step) {
;       const int c = seq * nch + (dir ? (nch - 1 - step) : step);
;       const size_t base = ((size_t)c * 8 + head) * 2 + dir;
;       unsigned* p = (unsigned*)(P.st + base * 16384 + dv * 128 + dk2 * 2);
;       const unsigned u = *p;
;       const float2 d = *(const float2*)(P.dt + base * 128 + dk2 * 2);
;       *p = pack2(s0, s1);
;       s0 = d.x * s0 + bflo(u); s1 = d.y * s1 + bfhi(u);
;     }
;   }
	global_load_dword v14, v[2:3], off
	global_load_dwordx2 v[22:23], v[4:5], off
	v_lshl_add_u64 v[2:3], v[2:3], 0, v[8:9]
	v_lshl_add_u64 v[4:5], v[4:5], 0, v[10:11]
	global_load_dword v15, v[2:3], off
	global_load_dwordx2 v[24:25], v[4:5], off
	v_lshl_add_u64 v[2:3], v[2:3], 0, v[8:9]
	v_lshl_add_u64 v[4:5], v[4:5], 0, v[10:11]
	global_load_dword v16, v[2:3], off
	global_load_dwordx2 v[26:27], v[4:5], off
	v_lshl_add_u64 v[2:3], v[2:3], 0, v[8:9]
	v_lshl_add_u64 v[4:5], v[4:5], 0, v[10:11]
	global_load_dword v17, v[2:3], off
	global_load_dwordx2 v[28:29], v[4:5], off
	v_lshl_add_u64 v[2:3], v[2:3], 0, v[8:9]
	v_lshl_add_u64 v[4:5], v[4:5], 0, v[10:11]
	global_load_dword v18, v[2:3], off
	global_load_dwordx2 v[30:31], v[4:5], off
	v_lshl_add_u64 v[2:3], v[2:3], 0, v[8:9]
	v_lshl_add_u64 v[4:5], v[4:5], 0, v[10:11]
	global_load_dword v19, v[2:3], off
	global_load_dwordx2 v[32:33], v[4:5], off
	v_lshl_add_u64 v[2:3], v[2:3], 0, v[8:9]
	v_lshl_add_u64 v[4:5], v[4:5], 0, v[10:11]
	global_load_dword v20, v[2:3], off
	global_load_dwordx2 v[34:35], v[4:5], off
	v_lshl_add_u64 v[2:3], v[2:3], 0, v[8:9]
	v_lshl_add_u64 v[4:5], v[4:5], 0, v[10:11]
	global_load_dword v21, v[2:3], off
	global_load_dwordx2 v[214:215], v[4:5], off
	v_lshl_add_u64 v[2:3], v[2:3], 0, v[8:9]
	v_lshl_add_u64 v[4:5], v[4:5], 0, v[10:11]
	v_cvt_pk_bf16_f32 v213, v6, v7
	global_store_dword v[12:13], v213, off
	v_lshl_add_u64 v[12:13], v[12:13], 0, v[8:9]
	s_waitcnt vmcnt(39)
	v_lshlrev_b32_e32 v0, 16, v216
	v_and_b32_e32 v216, 0xffff0000, v216
	v_fma_f32 v6, v6, v224, v0
	v_fma_f32 v7, v7, v225, v216
	v_cvt_pk_bf16_f32 v213, v6, v7
	global_store_dword v[12:13], v213, off
	v_lshl_add_u64 v[12:13], v[12:13], 0, v[8:9]
	s_waitcnt vmcnt(38)
	v_lshlrev_b32_e32 v0, 16, v217
	v_and_b32_e32 v217, 0xffff0000, v217
	v_fma_f32 v6, v6, v226, v0
	v_fma_f32 v7, v7, v227, v217
	v_cvt_pk_bf16_f32 v213, v6, v7
	global_store_dword v[12:13], v213, off
	v_lshl_add_u64 v[12:13], v[12:13], 0, v[8:9]
	s_waitcnt vmcnt(37)
	v_lshlrev_b32_e32 v0, 16, v218
	v_and_b32_e32 v218, 0xffff0000, v218
	v_fma_f32 v6, v6, v228, v0
	v_fma_f32 v7, v7, v229, v218
	v_cvt_pk_bf16_f32 v213, v6, v7
	global_store_dword v[12:13], v213, off
	v_lshl_add_u64 v[12:13], v[12:13], 0, v[8:9]
	s_waitcnt vmcnt(36)
	v_lshlrev_b32_e32 v0, 16, v219
	v_and_b32_e32 v219, 0xffff0000, v219
	v_fma_f32 v6, v6, v230, v0
	v_fma_f32 v7, v7, v231, v219
	v_cvt_pk_bf16_f32 v213, v6, v7
	global_store_dword v[12:13], v213, off
	v_lshl_add_u64 v[12:13], v[12:13], 0, v[8:9]
	s_waitcnt vmcnt(35)
	v_lshlrev_b32_e32 v0, 16, v220
	v_and_b32_e32 v220, 0xffff0000, v220
	v_fma_f32 v6, v6, v232, v0
	v_fma_f32 v7, v7, v233, v220
	v_cvt_pk_bf16_f32 v213, v6, v7
	global_store_dword v[12:13], v213, off
	v_lshl_add_u64 v[12:13], v[12:13], 0, v[8:9]
	s_waitcnt vmcnt(34)
	v_lshlrev_b32_e32 v0, 16, v221
	v_and_b32_e32 v221, 0xffff0000, v221
	v_fma_f32 v6, v6, v234, v0
	v_fma_f32 v7, v7, v235, v221
	v_cvt_pk_bf16_f32 v213, v6, v7
	global_store_dword v[12:13], v213, off
	v_lshl_add_u64 v[12:13], v[12:13], 0, v[8:9]
	s_waitcnt vmcnt(33)
	v_lshlrev_b32_e32 v0, 16, v222
	v_and_b32_e32 v222, 0xffff0000, v222
	v_fma_f32 v6, v6, v252, v0
	v_fma_f32 v7, v7, v253, v222
	v_cvt_pk_bf16_f32 v213, v6, v7
	global_store_dword v[12:13], v213, off
	v_lshl_add_u64 v[12:13], v[12:13], 0, v[8:9]
	s_waitcnt vmcnt(32)
	v_lshlrev_b32_e32 v0, 16, v223
	v_and_b32_e32 v223, 0xffff0000, v223
	v_fma_f32 v6, v6, v254, v0
	v_fma_f32 v7, v7, v255, v223
	s_branch .Lscan_loop
.Lscan_tail:
	v_cvt_pk_bf16_f32 v213, v6, v7
	global_store_dword v[12:13], v213, off
	v_lshl_add_u64 v[12:13], v[12:13], 0, v[8:9]
	s_waitcnt vmcnt(23)
	v_lshlrev_b32_e32 v0, 16, v216
	v_and_b32_e32 v216, 0xffff0000, v216
	v_fma_f32 v6, v6, v224, v0
	v_fma_f32 v7, v7, v225, v216
	v_cvt_pk_bf16_f32 v213, v6, v7
	global_store_dword v[12:13], v213, off
	v_lshl_add_u64 v[12:13], v[12:13], 0, v[8:9]
	s_waitcnt vmcnt(22)
	v_lshlrev_b32_e32 v0, 16, v217
	v_and_b32_e32 v217, 0xffff0000, v217
	v_fma_f32 v6, v6, v226, v0
	v_fma_f32 v7, v7, v227, v217
	v_cvt_pk_bf16_f32 v213, v6, v7
	global_store_dword v[12:13], v213, off
	v_lshl_add_u64 v[12:13], v[12:13], 0, v[8:9]
	s_waitcnt vmcnt(21)
	v_lshlrev_b32_e32 v0, 16, v218
	v_and_b32_e32 v218, 0xffff0000, v218
	v_fma_f32 v6, v6, v228, v0
	v_fma_f32 v7, v7, v229, v218
	v_cvt_pk_bf16_f32 v213, v6, v7
	global_store_dword v[12:13], v213, off
	v_lshl_add_u64 v[12:13], v[12:13], 0, v[8:9]
	s_waitcnt vmcnt(20)
	v_lshlrev_b32_e32 v0, 16, v219
	v_and_b32_e32 v219, 0xffff0000, v219
	v_fma_f32 v6, v6, v230, v0
	v_fma_f32 v7, v7, v231, v219
	v_cvt_pk_bf16_f32 v213, v6, v7
	global_store_dword v[12:13], v213, off
	v_lshl_add_u64 v[12:13], v[12:13], 0, v[8:9]
	s_waitcnt vmcnt(19)
	v_lshlrev_b32_e32 v0, 16, v220
	v_and_b32_e32 v220, 0xffff0000, v220
	v_fma_f32 v6, v6, v232, v0
	v_fma_f32 v7, v7, v233, v220
	v_cvt_pk_bf16_f32 v213, v6, v7
	global_store_dword v[12:13], v213, off
	v_lshl_add_u64 v[12:13], v[12:13], 0, v[8:9]
	s_waitcnt vmcnt(18)
	v_lshlrev_b32_e32 v0, 16, v221
	v_and_b32_e32 v221, 0xffff0000, v221
	v_fma_f32 v6, v6, v234, v0
	v_fma_f32 v7, v7, v235, v221
	v_cvt_pk_bf16_f32 v213, v6, v7
	global_store_dword v[12:13], v213, off
	v_lshl_add_u64 v[12:13], v[12:13], 0, v[8:9]
	s_waitcnt vmcnt(17)
	v_lshlrev_b32_e32 v0, 16, v222
	v_and_b32_e32 v222, 0xffff0000, v222
	v_fma_f32 v6, v6, v252, v0
	v_fma_f32 v7, v7, v253, v222
	v_cvt_pk_bf16_f32 v213, v6, v7
	global_store_dword v[12:13], v213, off
	v_lshl_add_u64 v[12:13], v[12:13], 0, v[8:9]
	s_waitcnt vmcnt(16)
	v_lshlrev_b32_e32 v0, 16, v223
	v_and_b32_e32 v223, 0xffff0000, v223
	v_fma_f32 v6, v6, v254, v0
	v_fma_f32 v7, v7, v255, v223
	v_add_u32_e32 v1, s28, v1
	v_cmp_le_i32_e32 vcc, s6, v1
	s_or_b64 s[2:3], vcc, s[2:3]
	s_andn2_b64 exec, exec, s[2:3]
	s_cbranch_execnz .LBB0_605

; DI int tid_opaque() { int t = threadIdx.x; asm volatile("" : "+v"(t)); return t; }
; DI f32x16 zero16() { f32x16 z; _Pragma("unroll") for (int i = 0; i < 16; ++i) z[i] = 0.f; return z; }
; DI void attn_item(const Params& P, int half, int item, char* smem) {
;   const int slen = half ? 16384 : 2048;
;   const int nqb = slen >> 8;
;   const int qb = item % nqb; const int head = (item / nqb) & 7; const int seq = item / (nqb * 8);
;   const int tid = tid_opaque(), lane = tid & 63, w = tid >> 6, r = lane & 31, h = lane >> 5;
;   const int qrow = seq * slen + qb * 256 + 32 * w + r;
;   bf16x8 qf[12];
;   _Pragma("unroll") for (int s = 0; s < 12; ++s)
;     qf[s] = *(const bf16x8*)(P.qfull + (size_t)qrow * 1536 + head * 192 + 16 * s + 8 * h);
;   f32x16 o[4]; o[0] = zero16(); o[1] = zero16(); o[2] = zero16(); o[3] = zero16();
;   float mrun = -1e30f, lrun = 0.f;
;   const int nkt = slen >> 6;
;   const int tkb = seq * slen;
;   const int rn = r & 15, rr8 = (r >> 1) & 7;
;   asm volatile("s_waitcnt vmcnt(0)" ::: "memory");
;   attn_dma_k(P, head, tkb, smem, 0, w, lane);
;   attn_dma_v(P, head, tkb, smem, 0, w, lane);
;   attn_dma_k(P, head, tkb + 64, smem, 1, w, lane);
;   attn_dma_v(P, head, tkb + 64, smem, 1, w, lane);
.LBB0_728:
	s_abs_i32 s11, s10
	s_mul_hi_u32 s12, s11, s8
	s_mul_i32 s13, s12, s7
	s_ashr_i32 s0, s10, 31
	s_sub_i32 s13, s11, s13
	s_xor_b32 s1, s0, s6
	s_add_i32 s14, s12, 1
	s_sub_i32 s15, s13, s7
	s_cmp_ge_u32 s13, s7
	s_cselect_b32 s12, s14, s12
	s_cselect_b32 s13, s15, s13
	s_add_i32 s14, s12, 1
	s_cmp_ge_u32 s13, s7
	s_cselect_b32 s12, s14, s12
	s_xor_b32 s12, s12, s1
	s_mul_hi_u32 s13, s11, s9
	s_sub_i32 s1, s12, s1
	s_mul_i32 s14, s13, s3
	s_mul_i32 s12, s1, s2
	s_sub_i32 s11, s11, s14
	s_sub_i32 s12, s10, s12
	s_and_b32 s1, s1, 7
	s_add_i32 s14, s13, 1
	s_sub_i32 s15, s11, s3
	s_cmp_ge_u32 s11, s3
	s_cselect_b32 s13, s14, s13
	s_cselect_b32 s11, s15, s11
	s_add_i32 s14, s13, 1
	s_cmp_ge_u32 s11, s3
	s_cselect_b32 s11, s14, s13
	s_xor_b32 s11, s11, s0
	s_sub_i32 s0, s11, s0
	v_mov_b32_e32 v16, v144
	s_lshl_b32 s0, s0, s4
	s_lshl_b32 s11, s12, 8
	s_add_i32 s11, s0, s11
	v_and_b32_e32 v17, 31, v16
	v_ashrrev_i32_e32 v4, 6, v16
	v_or_b32_e32 v0, s11, v17
	v_lshl_add_u32 v154, v4, 5, v0
	v_mov_b64_e32 v[0:1], s[18:19]
	s_movk_i32 s11, 0xc00
	v_readlane_b32 s14, v249, 0
	v_bfe_u32 v166, v16, 5, 1
	v_mad_i64_i32 v[0:1], s[12:13], v154, s11, v[0:1]
	v_readlane_b32 s15, v249, 1
	s_mul_i32 s14, s1, 0x180
	v_lshlrev_b32_e32 v152, 4, v166
	v_lshl_add_u64 v[0:1], v[0:1], 0, s[14:15]
	v_lshl_add_u64 v[0:1], v[0:1], 0, v[152:153]
	global_load_dwordx4 v[96:99], v[0:1], off
	global_load_dwordx4 v[100:103], v[0:1], off offset:32
	global_load_dwordx4 v[104:107], v[0:1], off offset:64
	global_load_dwordx4 v[108:111], v[0:1], off offset:96
	global_load_dwordx4 v[112:115], v[0:1], off offset:128
	global_load_dwordx4 v[116:119], v[0:1], off offset:160
	global_load_dwordx4 v[120:123], v[0:1], off offset:192
	global_load_dwordx4 v[124:127], v[0:1], off offset:224
	global_load_dwordx4 v[128:131], v[0:1], off offset:256
	global_load_dwordx4 v[132:135], v[0:1], off offset:288
	global_load_dwordx4 v[136:139], v[0:1], off offset:320
	global_load_dwordx4 v[140:143], v[0:1], off offset:352
	v_bfe_u32 v3, v16, 4, 2
	v_lshlrev_b32_e32 v0, 2, v4
	v_and_b32_e32 v2, 63, v16
	v_or_b32_e32 v169, v0, v3
	v_lshlrev_b32_e32 v168, 4, v2
	v_bitop3_b32 v2, v0, v16, v3 bitop3:0x36
	v_add_u32_e32 v0, s0, v169
	v_ashrrev_i32_e32 v1, 31, v0
	v_add_u32_e32 v5, 0, v168
	v_lshlrev_b64 v[0:1], 11, v[0:1]
	v_lshlrev_b32_e32 v170, 10, v4
	v_lshl_add_u64 v[0:1], s[20:21], 0, v[0:1]
	s_lshl_b32 s14, s1, 8
	v_lshlrev_b32_e32 v2, 4, v2
	v_add_u32_e32 v21, v5, v170
	s_lshl_b32 s11, s1, 7
	v_lshl_add_u64 v[0:1], v[0:1], 0, s[14:15]
	v_and_b32_e32 v152, 0xf0, v2
	v_readfirstlane_b32 s1, v21
	s_waitcnt vmcnt(0)
	v_lshl_add_u64 v[0:1], v[0:1], 0, v[152:153]
	s_mov_b32 m0, s1
	v_add_u32_e32 v8, 8, v4
	global_load_lds_dwordx4 v[0:1], off
	v_lshlrev_b32_e32 v0, 2, v8
	v_or_b32_e32 v22, v0, v3
	v_bitop3_b32 v2, v0, v16, v3 bitop3:0x36
	v_add_u32_e32 v0, s0, v22
	v_ashrrev_i32_e32 v1, 31, v0
	v_lshlrev_b64 v[0:1], 11, v[0:1]
	v_lshlrev_b32_e32 v171, 10, v8
	v_lshl_add_u64 v[0:1], s[20:21], 0, v[0:1]
	v_lshlrev_b32_e32 v2, 4, v2
	v_add_u32_e32 v23, v5, v171
	v_lshl_add_u64 v[0:1], v[0:1], 0, s[14:15]
	v_and_b32_e32 v2, 0xf0, v2
	v_mov_b32_e32 v3, v153
	v_readfirstlane_b32 s1, v23
	v_bfe_u32 v9, v16, 3, 3
	v_lshl_add_u64 v[0:1], v[0:1], 0, v[2:3]
	s_mov_b32 m0, s1
	v_lshl_or_b32 v172, v4, 3, v9
	global_load_lds_dwordx4 v[0:1], off
	v_lshrrev_b32_e32 v0, 1, v172
	v_xor_b32_e32 v4, v0, v16
	v_add_u32_e32 v0, s0, v172
	v_ashrrev_i32_e32 v1, 31, v0
	v_add3_u32 v24, 0, v170, v168
	v_lshlrev_b64 v[0:1], 7, v[0:1]
	v_lshlrev_b32_e32 v4, 4, v4
	v_add_u32_e32 v6, 0x4000, v24
	v_lshl_add_u64 v[0:1], s[50:51], 0, v[0:1]
	v_and_b32_e32 v4, 0x70, v4
	v_mov_b32_e32 v5, v153
	v_readfirstlane_b32 s1, v6
	v_lshl_add_u64 v[0:1], v[0:1], 0, v[4:5]
	s_mov_b32 m0, s1
	s_ashr_i32 s1, s0, 31
	global_load_lds_dwordx4 v[0:1], off
	v_add_u32_e32 v0, s11, v172
	v_ashrrev_i32_e32 v1, 31, v0
	v_lshlrev_b64 v[0:1], 15, v[0:1]
	v_lshl_add_u64 v[0:1], s[22:23], 0, v[0:1]
	s_lshl_b64 s[12:13], s[0:1], 1
	v_add_u32_e32 v10, 0x6000, v21
	v_lshl_add_u64 v[6:7], v[0:1], 0, s[12:13]
	v_readfirstlane_b32 s1, v10
	v_add_u32_e32 v14, 0x6000, v23
	v_lshl_add_u64 v[6:7], v[6:7], 0, v[4:5]
	s_mov_b32 m0, s1
	v_lshl_or_b32 v8, v8, 3, v9
	v_readfirstlane_b32 s1, v14
	global_load_lds_dwordx4 v[6:7], off
	v_lshrrev_b32_e32 v9, 1, v8
	v_add_u32_e32 v8, s11, v8
	s_mov_b32 m0, s1
	s_or_b32 s1, s0, 64
	v_xor_b32_e32 v12, v9, v16
	v_ashrrev_i32_e32 v9, 31, v8
	v_add_u32_e32 v14, s1, v169
	v_lshlrev_b64 v[8:9], 15, v[8:9]
	v_ashrrev_i32_e32 v15, 31, v14
	v_lshl_add_u64 v[8:9], s[22:23], 0, v[8:9]
	v_lshlrev_b32_e32 v12, 4, v12
	v_lshlrev_b64 v[14:15], 11, v[14:15]
	v_lshl_add_u64 v[10:11], v[8:9], 0, s[12:13]
	v_and_b32_e32 v12, 0x70, v12
	v_mov_b32_e32 v13, v153
	v_lshl_add_u64 v[14:15], s[20:21], 0, v[14:15]
	v_add_u32_e32 v21, 0xa000, v21
	v_lshl_add_u64 v[10:11], v[10:11], 0, v[12:13]
	v_lshl_add_u64 v[14:15], v[14:15], 0, s[14:15]
	v_readfirstlane_b32 s12, v21
	global_load_lds_dwordx4 v[10:11], off
	v_lshl_add_u64 v[14:15], v[14:15], 0, v[152:153]
	s_mov_b32 m0, s12
	v_add_u32_e32 v21, 0xa000, v23
	global_load_lds_dwordx4 v[14:15], off
	v_add_u32_e32 v14, s1, v22
	v_ashrrev_i32_e32 v15, 31, v14
	v_lshlrev_b64 v[14:15], 11, v[14:15]
	v_lshl_add_u64 v[14:15], s[20:21], 0, v[14:15]
	v_lshl_add_u64 v[14:15], v[14:15], 0, s[14:15]
	v_readfirstlane_b32 s12, v21
	v_lshl_add_u64 v[14:15], v[14:15], 0, v[2:3]
	s_mov_b32 m0, s12
	v_add_u32_e32 v21, 0xe000, v24
	global_load_lds_dwordx4 v[14:15], off
	v_add_u32_e32 v14, s1, v172
	v_ashrrev_i32_e32 v15, 31, v14
	v_lshlrev_b64 v[14:15], 7, v[14:15]
	v_lshl_add_u64 v[14:15], s[50:51], 0, v[14:15]
; DI f32x16 zero16() { f32x16 z; _Pragma("unroll") for (int i = 0; i < 16; ++i) z[i] = 0.f; return z; }
; DI void attn_dma_k(const Params& P, int head, int tk0, char* smem, int stage, int w, int lane) {
;   _Pragma("unroll") for (int i = 0; i < 2; ++i) {
;     const int idx = w + 8 * i;
;     const int row = 4 * idx + (lane >> 4), pos = lane & 15;
;     const int c = pos ^ (row & 15);
;     const bf16_t* g = P.knope + (size_t)(tk0 + row) * 1024 + head * 128 + c * 8;
;     __builtin_amdgcn_global_load_lds((const unsigned*)g, (unsigned*)(smem + stage * 40960 + idx * 1024 + lane * 16), 16, 0, 0);
;   }
;   {
;     const int i = 0; (void)i;
;     const int idx = w;
;     const int row = 8 * idx + (lane >> 3), pos = lane & 7;
;     const int c = pos ^ ((row >> 1) & 7);
;     const bf16_t* g = P.kr + (size_t)(tk0 + row) * 64 + c * 8;
;     __builtin_amdgcn_global_load_lds((const unsigned*)g, (unsigned*)(smem + stage * 40960 + 16384 + idx * 1024 + lane * 16), 16, 0, 0);
;   }
; }
; DI void attn_dma_v(const Params& P, int head, int tk0, char* smem, int vstage, int w, int lane) {
;   _Pragma("unroll") for (int i = 0; i < 2; ++i) {
;     const int idx = w + 8 * i;
;     const int row = 8 * idx + (lane >> 3), pos = lane & 7;
;     const int c = pos ^ ((row >> 1) & 7);
;     const bf16_t* g = P.vt + (size_t)(head * 128 + row) * TH + tk0 + c * 8;
;     __builtin_amdgcn_global_load_lds((const unsigned*)g, (unsigned*)(smem + vstage * 40960 + 24576 + idx * 1024 + lane * 16), 16, 0, 0);
;   }
; }
; DI void attn_item(const Params& P, int half, int item, char* smem) {
;     ...
;   bf16x8 qf[12];
;   _Pragma("unroll") for (int s = 0; s < 12; ++s)
;     qf[s] = *(const bf16x8*)(P.qfull + (size_t)qrow * 1536 + head * 192 + 16 * s + 8 * h);
;   f32x16 o[4]; o[0] = zero16(); o[1] = zero16(); o[2] = zero16(); o[3] = zero16();
;   float mrun = -1e30f, lrun = 0.f;
;   const int nkt = slen >> 6;
;   const int tkb = seq * slen;
;   const int rn = r & 15, rr8 = (r >> 1) & 7;
;   asm volatile("s_waitcnt vmcnt(0)" ::: "memory");
;   attn_dma_k(P, head, tkb, smem, 0, w, lane);
;   attn_dma_v(P, head, tkb, smem, 0, w, lane);
;   attn_dma_k(P, head, tkb + 64, smem, 1, w, lane);
;   attn_dma_v(P, head, tkb + 64, smem, 1, w, lane);
;   int cur = 0;
	v_readfirstlane_b32 s1, v21
	v_lshl_add_u64 v[14:15], v[14:15], 0, v[4:5]
	s_mov_b32 m0, s1
	s_add_i32 s1, 0, 0x10000
	global_load_lds_dwordx4 v[14:15], off
	v_add_u32_e32 v14, s1, v168
	v_add_u32_e32 v15, v14, v170
	s_mov_b64 s[12:13], 0x80
	v_readfirstlane_b32 s1, v15
	v_lshl_add_u64 v[6:7], v[6:7], 0, s[12:13]
	s_mov_b32 m0, s1
	v_and_b32_e32 v18, 15, v16
	global_load_lds_dwordx4 v[6:7], off
	v_lshl_add_u64 v[6:7], v[10:11], 0, s[12:13]
	v_add_u32_e32 v10, v14, v171
	v_lshrrev_b32_e32 v19, 1, v16
	v_readfirstlane_b32 s1, v10
	s_mov_b32 m0, s1
	v_bfe_u32 v20, v16, 1, 3
	global_load_lds_dwordx4 v[6:7], off
	v_bitop3_b32 v6, v166, v16, 15 bitop3:0x78
	v_lshlrev_b32_e32 v175, 4, v6
	v_bitop3_b32 v6, v166, v18, 2 bitop3:0x36
	v_lshlrev_b32_e32 v176, 4, v6
	v_bitop3_b32 v6, v166, v18, 4 bitop3:0x36
	v_lshlrev_b32_e32 v177, 4, v6
	v_bitop3_b32 v6, v166, v18, 6 bitop3:0x36
	v_lshlrev_b32_e32 v178, 4, v6
	v_bitop3_b32 v6, v166, v18, 8 bitop3:0x36
	v_lshlrev_b32_e32 v179, 4, v6
	v_bitop3_b32 v6, v166, v18, 10 bitop3:0x36
	v_lshlrev_b32_e32 v180, 4, v6
	v_bitop3_b32 v6, v166, v18, 12 bitop3:0x36
	v_lshlrev_b32_e32 v181, 4, v6
	v_bitop3_b32 v6, v166, v18, 14 bitop3:0x36
	v_lshlrev_b32_e32 v182, 4, v6
	v_bitop3_b32 v6, v166, v19, 7 bitop3:0x78
	v_lshlrev_b32_e32 v183, 4, v6
	v_bitop3_b32 v6, v166, v20, 2 bitop3:0x36
	v_lshlrev_b32_e32 v184, 4, v6
	v_bitop3_b32 v6, v166, v20, 4 bitop3:0x36
	v_writelane_b32 v249, s14, 0
	s_add_u32 s12, s20, s14
	v_lshlrev_b32_e32 v185, 4, v6
	v_bitop3_b32 v6, v166, v20, 6 bitop3:0x36
	v_lshlrev_b32_e32 v187, 4, v20
	s_addc_u32 s13, s21, 0
	v_mov_b32_e32 v64, 0
	v_ashrrev_i32_e32 v155, 31, v154
	v_lshlrev_b32_e32 v167, 3, v166
	v_lshlrev_b32_e32 v173, 8, v17
	v_lshlrev_b32_e32 v174, 7, v17
	v_lshlrev_b32_e32 v186, 4, v6
	v_xor_b32_e32 v188, 16, v187
	v_xor_b32_e32 v189, 32, v187
	v_xor_b32_e32 v190, 48, v187
	v_xor_b32_e32 v191, 64, v187
	v_xor_b32_e32 v192, 0x50, v187
	v_xor_b32_e32 v193, 0x60, v187
	v_xor_b32_e32 v194, 0x70, v187
	v_lshl_add_u64 v[156:157], s[12:13], 0, v[152:153]
	v_lshl_add_u64 v[158:159], s[12:13], 0, v[2:3]
	v_lshl_add_u64 v[160:161], s[50:51], 0, v[4:5]
	v_lshl_add_u64 v[162:163], v[0:1], 0, v[4:5]
	v_lshl_add_u64 v[164:165], v[8:9], 0, v[12:13]
	v_lshlrev_b32_e32 v252, 11, v169
	v_mov_b32_e32 v253, 0
	v_lshl_add_u64 v[156:157], v[156:157], 0, v[252:253]
	v_add_u32_e32 v252, 0x10000, v252
	v_readfirstlane_b32 s82, v170
	v_lshl_add_u64 v[158:159], v[158:159], 0, v[252:253]
	v_lshlrev_b32_e32 v252, 7, v172
	s_nop 0
	v_lshl_add_u64 v[160:161], v[160:161], 0, v[252:253]
	s_addk_i32 s0, 0x80
	s_mov_b32 s13, 0
	v_mov_b32_e32 v196, 0xf149f2ca
	s_mov_b32 s12, s5
	v_mov_b32_e32 v0, 0
	v_mov_b32_e32 v1, v64
	v_mov_b32_e32 v2, v64
	v_mov_b32_e32 v3, v64
	v_mov_b32_e32 v4, v64
	v_mov_b32_e32 v5, v64
	v_mov_b32_e32 v6, v64
	v_mov_b32_e32 v7, v64
	v_mov_b32_e32 v8, v64
	v_mov_b32_e32 v9, v64
	v_mov_b32_e32 v10, v64
	v_mov_b32_e32 v11, v64
	v_mov_b32_e32 v12, v64
	v_mov_b32_e32 v13, v64
	v_mov_b32_e32 v14, v64
	v_mov_b32_e32 v15, v64
	v_mov_b32_e32 v16, 0
	v_mov_b32_e32 v17, v64
	v_mov_b32_e32 v18, v64
	v_mov_b32_e32 v19, v64
	v_mov_b32_e32 v20, v64
	v_mov_b32_e32 v21, v64
	v_mov_b32_e32 v22, v64
	v_mov_b32_e32 v23, v64
	v_mov_b32_e32 v24, v64
	v_mov_b32_e32 v25, v64
	v_mov_b32_e32 v26, v64
	v_mov_b32_e32 v27, v64
	v_mov_b32_e32 v28, v64
	v_mov_b32_e32 v29, v64
	v_mov_b32_e32 v30, v64
	v_mov_b32_e32 v31, v64
	v_mov_b32_e32 v32, 0
	v_mov_b32_e32 v33, v64
	v_mov_b32_e32 v34, v64
	v_mov_b32_e32 v35, v64
	v_mov_b32_e32 v36, v64
	v_mov_b32_e32 v37, v64
	v_mov_b32_e32 v38, v64
	v_mov_b32_e32 v39, v64
	v_mov_b32_e32 v40, v64
	v_mov_b32_e32 v41, v64
	v_mov_b32_e32 v42, v64
	v_mov_b32_e32 v43, v64
	v_mov_b32_e32 v44, v64
	v_mov_b32_e32 v45, v64
	v_mov_b32_e32 v46, v64
	v_mov_b32_e32 v47, v64
	v_mov_b32_e32 v48, 0
	v_mov_b32_e32 v49, v64
	v_mov_b32_e32 v50, v64
	v_mov_b32_e32 v51, v64
	v_mov_b32_e32 v52, v64
	v_mov_b32_e32 v53, v64
	v_mov_b32_e32 v54, v64
	v_mov_b32_e32 v55, v64
	v_mov_b32_e32 v56, v64
	v_mov_b32_e32 v57, v64
	v_mov_b32_e32 v58, v64
	v_mov_b32_e32 v59, v64
	v_mov_b32_e32 v60, v64
	v_mov_b32_e32 v61, v64
	v_mov_b32_e32 v62, v64
	v_mov_b32_e32 v63, v64
	s_movk_i32 s17, 0x4000
	v_writelane_b32 v249, s15, 1
	s_waitcnt vmcnt(0)
; DI void attn_dma_k(const Params& P, int head, int tk0, char* smem, int stage, int w, int lane) {
;   _Pragma("unroll") for (int i = 0; i < 2; ++i) {
;     const int idx = w + 8 * i;
;     const int row = 4 * idx + (lane >> 4), pos = lane & 15;
;     const int c = pos ^ (row & 15);
;     const bf16_t* g = P.knope + (size_t)(tk0 + row) * 1024 + head * 128 + c * 8;
;     __builtin_amdgcn_global_load_lds((const unsigned*)g, (unsigned*)(smem + stage * 40960 + idx * 1024 + lane * 16), 16, 0, 0);
;   }
;   {
;     const int i = 0; (void)i;
;     const int idx = w;
;     const int row = 8 * idx + (lane >> 3), pos = lane & 7;
;     const int c = pos ^ ((row >> 1) & 7);
;     const bf16_t* g = P.kr + (size_t)(tk0 + row) * 64 + c * 8;
;     __builtin_amdgcn_global_load_lds((const unsigned*)g, (unsigned*)(smem + stage * 40960 + 16384 + idx * 1024 + lane * 16), 16, 0, 0);
;   }
; }
; DI void attn_dma_v(const Params& P, int head, int tk0, char* smem, int vstage, int w, int lane) {
;   _Pragma("unroll") for (int i = 0; i < 2; ++i) {
;     const int idx = w + 8 * i;
;     const int row = 8 * idx + (lane >> 3), pos = lane & 7;
;     const int c = pos ^ ((row >> 1) & 7);
; DI void attn_item(const Params& P, int half, int item, char* smem) {
;     ...
;   for (int kt = 0; kt < nkt; ++kt) {
;     asm volatile("s_waitcnt vmcnt(5) lgkmcnt(0)" ::: "memory");
;     __builtin_amdgcn_s_barrier();
;     {
;       const int nxt = (cur == 0) ? 2 : cur - 1;
;       attn_dma_k(P, head, tkb + (kt + 2) * 64, smem, nxt, w, lane);
;       attn_dma_v(P, head, tkb + (kt + 2) * 64, smem, nxt, w, lane);
;     }
;     const char* kn = smem + cur * 40960;
;     const char* kr = kn + 16384;
;     f32x16 st[2]; st[0] = zero16(); st[1] = zero16();
;     _Pragma("unroll") for (int s = 0; s < 8; ++s) {
;       const int po = ((2 * s + h) ^ rn) << 4;
;       bf16x8 a0 = *(const bf16x8*)(kn + r * 256 + po);
;       bf16x8 a1 = *(const bf16x8*)(kn + (32 + r) * 256 + po);
;       st[0] = MFMA32(a0, qf[s], st[0]);
;       st[1] = MFMA32(a1, qf[s], st[1]);
;     }
;     _Pragma("unroll") for (int s = 0; s < 4; ++s) {
;       const int po = ((2 * s + h) ^ rr8) << 4;
;       bf16x8 a0 = *(const bf16x8*)(kr + r * 128 + po);
;       bf16x8 a1 = *(const bf16x8*)(kr + (32 + r) * 128 + po);
;       st[0] = MFMA32(a0, qf[8 + s], st[0]);
;       st[1] = MFMA32(a1, qf[8 + s], st[1]);
;     }
.LBB0_729:
	s_mul_i32 s16, s13, 0xa000
	s_add_i32 s1, s16, 0xffff6000
	s_cmp_lg_u32 s13, 0
	s_cselect_b32 s1, s1, 0x14000
	v_mov_b32_e32 v197, v64
	s_add_u32 s80, s1, s82
	s_add_u32 s81, s80, 0x2000
	s_add_u32 s83, s80, 0x4000
	s_add_u32 s90, s80, 0x6000
	s_add_u32 s91, s80, 0x8000
	s_lshl_b32 s84, s0, 11
	s_mov_b32 s85, 0
	s_lshl_b32 s86, s0, 7
	s_mov_b32 s87, 0
	s_ashr_i32 s1, s0, 31
	s_lshl_b64 s[14:15], s[0:1], 1
	s_mov_b32 s1, s16
	v_add_u32_e32 v152, s1, v173
	s_waitcnt vmcnt(5) lgkmcnt(0)
	s_barrier
	v_add_u32_e32 v68, v152, v175
	ds_read_b128 v[64:67], v68
	ds_read_b128 v[68:71], v68 offset:8192
	s_waitcnt lgkmcnt(0)
	v_mfma_f32_32x32x16_bf16 v[80:95], v[64:67], v[96:99], 0
	v_add_u32_e32 v195, v152, v176
	ds_read_b128 v[206:209], v195
	ds_read_b128 v[210:213], v195 offset:8192
	s_mov_b32 m0, s80
	v_lshl_add_u64 v[252:253], v[156:157], 0, s[84:85]
	global_load_lds_dwordx4 v[252:253], off
	v_add_u32_e32 v195, v152, v177
	v_add_u32_e32 v205, s1, v174
	v_cmp_lt_i32_e32 vcc, v199, v198
	s_add_i32 s1, s13, 1
	s_cmp_lg_u32 s13, 2
	v_mfma_f32_32x32x16_bf16 v[64:79], v[68:71], v[96:99], 0
	s_cselect_b32 s13, s1, 0
	s_add_i32 s12, s12, -1
	s_add_i32 s0, s0, 64
	s_cmp_lg_u32 s12, 0
	s_waitcnt lgkmcnt(0)
	v_mfma_f32_32x32x16_bf16 v[80:95], v[206:209], v[100:103], v[80:95]
	v_mfma_f32_32x32x16_bf16 v[64:79], v[210:213], v[100:103], v[64:79]
	ds_read_b128 v[206:209], v195
	ds_read_b128 v[210:213], v195 offset:8192
	v_add_u32_e32 v195, v152, v178
	s_waitcnt lgkmcnt(0)
	v_mfma_f32_32x32x16_bf16 v[80:95], v[206:209], v[104:107], v[80:95]
	v_mfma_f32_32x32x16_bf16 v[64:79], v[210:213], v[104:107], v[64:79]
	ds_read_b128 v[206:209], v195
	ds_read_b128 v[210:213], v195 offset:8192
	s_mov_b32 m0, s81
	v_lshl_add_u64 v[254:255], v[158:159], 0, s[84:85]
	global_load_lds_dwordx4 v[254:255], off
	v_add_u32_e32 v195, v152, v179
	s_waitcnt lgkmcnt(0)
	v_mfma_f32_32x32x16_bf16 v[80:95], v[206:209], v[108:111], v[80:95]
	v_mfma_f32_32x32x16_bf16 v[64:79], v[210:213], v[108:111], v[64:79]
	ds_read_b128 v[206:209], v195
	ds_read_b128 v[210:213], v195 offset:8192
	v_add_u32_e32 v195, v152, v180
	s_waitcnt lgkmcnt(0)
	v_mfma_f32_32x32x16_bf16 v[80:95], v[206:209], v[112:115], v[80:95]
	v_mfma_f32_32x32x16_bf16 v[64:79], v[210:213], v[112:115], v[64:79]
	ds_read_b128 v[206:209], v195
	ds_read_b128 v[210:213], v195 offset:8192
	s_mov_b32 m0, s83
	v_lshl_add_u64 v[252:253], v[160:161], 0, s[86:87]
	global_load_lds_dwordx4 v[252:253], off
	v_add_u32_e32 v195, v152, v181
	v_add_u32_e32 v152, v152, v182
	s_waitcnt lgkmcnt(0)
	v_mfma_f32_32x32x16_bf16 v[80:95], v[206:209], v[116:119], v[80:95]
	v_mfma_f32_32x32x16_bf16 v[64:79], v[210:213], v[116:119], v[64:79]
	ds_read_b128 v[206:209], v195
	ds_read_b128 v[210:213], v195 offset:8192
	s_waitcnt lgkmcnt(0)
	v_mfma_f32_32x32x16_bf16 v[80:95], v[206:209], v[120:123], v[80:95]
	v_mfma_f32_32x32x16_bf16 v[64:79], v[210:213], v[120:123], v[64:79]
	ds_read_b128 v[206:209], v152
	ds_read_b128 v[210:213], v152 offset:8192
	s_mov_b32 m0, s90
	v_lshl_add_u64 v[254:255], v[162:163], 0, s[14:15]
	global_load_lds_dwordx4 v[254:255], off
	v_add_u32_e32 v152, v205, v183
	s_waitcnt lgkmcnt(0)
	v_mfma_f32_32x32x16_bf16 v[80:95], v[206:209], v[124:127], v[80:95]
	v_mfma_f32_32x32x16_bf16 v[64:79], v[210:213], v[124:127], v[64:79]
	ds_read_b128 v[206:209], v152 offset:16384
	ds_read_b128 v[210:213], v152 offset:20480
	v_add_u32_e32 v152, v205, v184
	s_waitcnt lgkmcnt(0)
	v_mfma_f32_32x32x16_bf16 v[80:95], v[206:209], v[128:131], v[80:95]
	v_mfma_f32_32x32x16_bf16 v[64:79], v[210:213], v[128:131], v[64:79]
	ds_read_b128 v[206:209], v152 offset:16384
	ds_read_b128 v[210:213], v152 offset:20480
	s_mov_b32 m0, s91
	v_lshl_add_u64 v[252:253], v[164:165], 0, s[14:15]
	global_load_lds_dwordx4 v[252:253], off
	v_add_u32_e32 v152, v205, v185
	s_waitcnt lgkmcnt(0)
	v_mfma_f32_32x32x16_bf16 v[80:95], v[206:209], v[132:135], v[80:95]
	v_mfma_f32_32x32x16_bf16 v[64:79], v[210:213], v[132:135], v[64:79]
	ds_read_b128 v[206:209], v152 offset:16384
	ds_read_b128 v[210:213], v152 offset:20480
	v_add_u32_e32 v152, v205, v186
	v_add_u32_e32 v205, v205, v167
	s_waitcnt lgkmcnt(0)
	v_mfma_f32_32x32x16_bf16 v[80:95], v[206:209], v[136:139], v[80:95]
	v_mfma_f32_32x32x16_bf16 v[64:79], v[210:213], v[136:139], v[64:79]
	ds_read_b128 v[206:209], v152 offset:16384
	ds_read_b128 v[210:213], v152 offset:20480
	s_waitcnt lgkmcnt(0)
	v_mfma_f32_32x32x16_bf16 v[80:95], v[206:209], v[140:143], v[80:95]
	v_mfma_f32_32x32x16_bf16 v[64:79], v[210:213], v[140:143], v[64:79]
	s_nop 10
	v_max_f32_e32 v195, v80, v80
	v_max_f32_e32 v152, v64, v64
	v_max_f32_e32 v152, v195, v152
	v_max3_f32 v152, v152, v81, v65
	v_max3_f32 v152, v152, v82, v66
	v_max3_f32 v152, v152, v83, v67
	v_max3_f32 v152, v152, v84, v68
	v_max3_f32 v152, v152, v85, v69
	v_max3_f32 v152, v152, v86, v70
	v_max3_f32 v152, v152, v87, v71
	v_max3_f32 v152, v152, v88, v72
	v_max3_f32 v152, v152, v89, v73
	v_max3_f32 v152, v152, v90, v74
	v_max3_f32 v152, v152, v91, v75
	v_max3_f32 v152, v152, v92, v76
	v_max3_f32 v152, v152, v93, v77
	v_max3_f32 v152, v152, v94, v78
	v_max3_f32 v195, v152, v95, v79
	v_cndmask_b32_e32 v152, v145, v199, vcc
	v_lshlrev_b32_e32 v152, 2, v152
	ds_bpermute_b32 v206, v152, v195
	s_waitcnt lgkmcnt(0)
; #define MFMA32(a, b, c) __builtin_amdgcn_mfma_f32_32x32x16_bf16((a), (b), (c), 0, 0, 0)
; DI void attn_item(const Params& P, int half, int item, char* smem) {
;     ...
;     float mx = st[0][0];
;     _Pragma("unroll") for (int i = 0; i < 16; ++i) { mx = fmaxf(mx, st[0][i]); mx = fmaxf(mx, st[1][i]); }
;     mx = fmaxf(mx, __shfl_xor(mx, 32));
;     const float mnew = fmaxf(mrun, mx);
;     const float alpha = __builtin_amdgcn_exp2f(mrun - mnew);
;     mrun = mnew;
;     float psum = 0.f;
;     _Pragma("unroll") for (int i = 0; i < 16; ++i) {
;       st[0][i] = __builtin_amdgcn_exp2f(st[0][i] - mnew); psum += st[0][i];
;       st[1][i] = __builtin_amdgcn_exp2f(st[1][i] - mnew); psum += st[1][i];
;     }
;     lrun = lrun * alpha + psum;
;     _Pragma("unroll") for (int mt = 0; mt < 4; ++mt) {
;       _Pragma("unroll") for (int i = 0; i < 16; ++i) o[mt][i] *= alpha;
;     }
;     const char* sv = smem + cur * 40960 + 24576;
;     _Pragma("unroll") for (int k2 = 0; k2 < 2; ++k2) {
;       _Pragma("unroll") for (int s2 = 0; s2 < 2; ++s2) {
;         bf16x8 pb = pack8(st[k2][8 * s2], st[k2][8 * s2 + 1], st[k2][8 * s2 + 2], st[k2][8 * s2 + 3],
;                           st[k2][8 * s2 + 4], st[k2][8 * s2 + 5], st[k2][8 * s2 + 6], st[k2][8 * s2 + 7]);
;         const int c0 = 4 * k2 + 2 * s2;
;         _Pragma("unroll") for (int mt = 0; mt < 4; ++mt) {
;           const char* vrow = sv + (32 * mt + r) * 128 + 8 * h;
;           s16x4 lo = *(const s16x4*)(vrow + ((c0 ^ rr8) << 4));
;           s16x4 hi = *(const s16x4*)(vrow + (((c0 + 1) ^ rr8) << 4));
;           bf16x8 va = __builtin_shufflevector(lo, hi, 0, 1, 2, 3, 4, 5, 6, 7);
;           o[mt] = MFMA32(va, pb, o[mt]);
;         }
;       }
;     }
	v_max3_f32 v195, v196, v195, v206
	v_sub_f32_e32 v64, v64, v195
	v_exp_f32_e32 v206, v64
	v_sub_f32_e32 v64, v81, v195
	v_exp_f32_e32 v81, v64
	v_sub_f32_e32 v64, v65, v195
	v_exp_f32_e32 v65, v64
	v_sub_f32_e32 v64, v82, v195
	v_exp_f32_e32 v82, v64
	v_sub_f32_e32 v64, v66, v195
	v_exp_f32_e32 v207, v64
	v_sub_f32_e32 v64, v83, v195
	v_exp_f32_e32 v83, v64
	v_sub_f32_e32 v64, v67, v195
	v_exp_f32_e32 v208, v64
	v_sub_f32_e32 v64, v84, v195
	v_exp_f32_e32 v84, v64
	v_sub_f32_e32 v64, v68, v195
	v_exp_f32_e32 v209, v64
	v_sub_f32_e32 v64, v85, v195
	v_exp_f32_e32 v68, v64
	v_sub_f32_e32 v64, v69, v195
	v_exp_f32_e32 v85, v64
	v_sub_f32_e32 v64, v86, v195
	v_exp_f32_e32 v69, v64
	v_sub_f32_e32 v64, v70, v195
	v_exp_f32_e32 v86, v64
	v_sub_f32_e32 v64, v87, v195
	v_exp_f32_e32 v70, v64
	v_sub_f32_e32 v64, v71, v195
	v_exp_f32_e32 v87, v64
	v_sub_f32_e32 v64, v88, v195
	v_exp_f32_e32 v88, v64
	v_sub_f32_e32 v64, v72, v195
	v_exp_f32_e32 v210, v64
	v_sub_f32_e32 v64, v89, v195
	v_exp_f32_e32 v89, v64
	v_sub_f32_e32 v64, v73, v195
	v_exp_f32_e32 v211, v64
	v_sub_f32_e32 v64, v90, v195
	v_exp_f32_e32 v90, v64
	v_sub_f32_e32 v64, v74, v195
	v_exp_f32_e32 v212, v64
	v_sub_f32_e32 v64, v91, v195
	v_exp_f32_e32 v91, v64
	v_sub_f32_e32 v64, v75, v195
	v_exp_f32_e32 v213, v64
	v_sub_f32_e32 v64, v92, v195
	v_exp_f32_e32 v92, v64
	v_sub_f32_e32 v64, v76, v195
	v_exp_f32_e32 v214, v64
	v_sub_f32_e32 v64, v93, v195
	v_sub_f32_e32 v80, v80, v195
	v_exp_f32_e32 v93, v64
	v_sub_f32_e32 v64, v77, v195
	v_exp_f32_e32 v80, v80
	v_exp_f32_e32 v215, v64
	v_sub_f32_e32 v64, v94, v195
	v_exp_f32_e32 v94, v64
	v_sub_f32_e32 v64, v78, v195
	v_exp_f32_e32 v216, v64
	v_sub_f32_e32 v64, v95, v195
	v_exp_f32_e32 v95, v64
	v_sub_f32_e32 v64, v79, v195
	v_exp_f32_e32 v217, v64
	v_sub_f32_e32 v196, v196, v195
	v_exp_f32_e32 v196, v196
	v_add_f32_e32 v64, 0, v80
	v_add_f32_e32 v64, v206, v64
	v_add_f32_e32 v64, v81, v64
	v_cmp_neq_f32_e32 vcc, 1.0, v196
	s_cbranch_vccz .Lattn_norescale
	v_pk_mul_f32 v[0:1], v[0:1], v[196:197] op_sel_hi:[1,0]
	v_pk_mul_f32 v[2:3], v[2:3], v[196:197] op_sel_hi:[1,0]
	v_pk_mul_f32 v[4:5], v[4:5], v[196:197] op_sel_hi:[1,0]
	v_pk_mul_f32 v[6:7], v[6:7], v[196:197] op_sel_hi:[1,0]
	v_pk_mul_f32 v[8:9], v[8:9], v[196:197] op_sel_hi:[1,0]
	v_pk_mul_f32 v[10:11], v[10:11], v[196:197] op_sel_hi:[1,0]
	v_pk_mul_f32 v[12:13], v[12:13], v[196:197] op_sel_hi:[1,0]
	v_pk_mul_f32 v[14:15], v[14:15], v[196:197] op_sel_hi:[1,0]
	v_pk_mul_f32 v[16:17], v[16:17], v[196:197] op_sel_hi:[1,0]
	v_pk_mul_f32 v[18:19], v[18:19], v[196:197] op_sel_hi:[1,0]
	v_pk_mul_f32 v[20:21], v[20:21], v[196:197] op_sel_hi:[1,0]
	v_pk_mul_f32 v[22:23], v[22:23], v[196:197] op_sel_hi:[1,0]
	v_pk_mul_f32 v[24:25], v[24:25], v[196:197] op_sel_hi:[1,0]
	v_pk_mul_f32 v[26:27], v[26:27], v[196:197] op_sel_hi:[1,0]
	v_pk_mul_f32 v[28:29], v[28:29], v[196:197] op_sel_hi:[1,0]
	v_pk_mul_f32 v[30:31], v[30:31], v[196:197] op_sel_hi:[1,0]
	v_pk_mul_f32 v[32:33], v[32:33], v[196:197] op_sel_hi:[1,0]
	v_pk_mul_f32 v[34:35], v[34:35], v[196:197] op_sel_hi:[1,0]
	v_pk_mul_f32 v[36:37], v[36:37], v[196:197] op_sel_hi:[1,0]
	v_pk_mul_f32 v[38:39], v[38:39], v[196:197] op_sel_hi:[1,0]
	v_pk_mul_f32 v[40:41], v[40:41], v[196:197] op_sel_hi:[1,0]
	v_pk_mul_f32 v[42:43], v[42:43], v[196:197] op_sel_hi:[1,0]
	v_pk_mul_f32 v[44:45], v[44:45], v[196:197] op_sel_hi:[1,0]
	v_pk_mul_f32 v[46:47], v[46:47], v[196:197] op_sel_hi:[1,0]
	v_pk_mul_f32 v[48:49], v[48:49], v[196:197] op_sel_hi:[1,0]
	v_pk_mul_f32 v[50:51], v[50:51], v[196:197] op_sel_hi:[1,0]
	v_pk_mul_f32 v[52:53], v[52:53], v[196:197] op_sel_hi:[1,0]
	v_pk_mul_f32 v[54:55], v[54:55], v[196:197] op_sel_hi:[1,0]
	v_pk_mul_f32 v[56:57], v[56:57], v[196:197] op_sel_hi:[1,0]
	v_pk_mul_f32 v[58:59], v[58:59], v[196:197] op_sel_hi:[1,0]
	v_pk_mul_f32 v[60:61], v[60:61], v[196:197] op_sel_hi:[1,0]
	v_pk_mul_f32 v[62:63], v[62:63], v[196:197] op_sel_hi:[1,0]
.Lattn_norescale:
	v_cvt_pk_bf16_f32 v66, v80, v81
	v_add_f32_e32 v64, v65, v64
	v_add_f32_e32 v64, v82, v64
	v_add_f32_e32 v64, v207, v64
	v_add_f32_e32 v64, v83, v64
	v_cvt_pk_bf16_f32 v67, v82, v83
	v_add_u32_e32 v71, v205, v187
	v_add_u32_e32 v251, v205, v188
	ds_read_b64 v[72:73], v71 offset:24576
	ds_read_b64 v[74:75], v251 offset:24576
	ds_read_b64 v[76:77], v71 offset:28672
	ds_read_b64 v[78:79], v251 offset:28672
	ds_read_b64 v[252:253], v71 offset:32768
	ds_read_b64 v[254:255], v251 offset:32768
	ds_read_b64 v[80:81], v71 offset:36864
	ds_read_b64 v[82:83], v251 offset:36864
	v_add_f32_e32 v64, v208, v64
	v_add_f32_e32 v64, v84, v64
	v_add_f32_e32 v64, v209, v64
	v_add_f32_e32 v64, v68, v64
	v_add_f32_e32 v64, v85, v64
	v_add_f32_e32 v64, v69, v64
	v_add_f32_e32 v64, v86, v64
	v_add_f32_e32 v64, v70, v64
	v_cvt_pk_bf16_f32 v68, v84, v68
	v_cvt_pk_bf16_f32 v69, v69, v70
	v_add_f32_e32 v64, v87, v64
	s_waitcnt lgkmcnt(4)
	v_mfma_f32_32x32x16_bf16 v[48:63], v[72:75], v[66:69], v[48:63]
	v_mfma_f32_32x32x16_bf16 v[32:47], v[76:79], v[66:69], v[32:47]
	v_add_u32_e32 v71, v205, v189
	v_add_u32_e32 v251, v205, v190
	ds_read_b64 v[72:73], v71 offset:24576
	ds_read_b64 v[74:75], v251 offset:24576
	ds_read_b64 v[76:77], v71 offset:28672
	ds_read_b64 v[78:79], v251 offset:28672
	v_add_f32_e32 v64, v88, v64
	v_add_f32_e32 v64, v210, v64
	s_waitcnt lgkmcnt(4)
	v_mfma_f32_32x32x16_bf16 v[16:31], v[252:255], v[66:69], v[16:31]
	v_mfma_f32_32x32x16_bf16 v[0:15], v[80:83], v[66:69], v[0:15]
	v_cvt_pk_bf16_f32 v66, v88, v89
	v_cvt_pk_bf16_f32 v67, v90, v91
	v_cvt_pk_bf16_f32 v68, v92, v93
	v_cvt_pk_bf16_f32 v69, v94, v95
	ds_read_b64 v[252:253], v71 offset:32768
	ds_read_b64 v[254:255], v251 offset:32768
	ds_read_b64 v[80:81], v71 offset:36864
	ds_read_b64 v[82:83], v251 offset:36864
	v_add_f32_e32 v64, v89, v64
	v_add_f32_e32 v64, v211, v64
	s_waitcnt lgkmcnt(4)
; #define MFMA32(a, b, c) __builtin_amdgcn_mfma_f32_32x32x16_bf16((a), (b), (c), 0, 0, 0)
; DI unsigned pack2(float a, float b) { f32x2_t v = {a, b}; return __builtin_bit_cast(unsigned, __builtin_convertvector(v, bf16x2_t)); }
; DI float bflo(unsigned p) { return __uint_as_float(p << 16); }
; DI float bfhi(unsigned p) { return __uint_as_float(p & 0xffff0000u); }
; DI float siluf_(float x) { return x * frcp(1.f + __expf(-x)); }
; DI void attn_item(const Params& P, int half, int item, char* smem) {
;     ...
;     _Pragma("unroll") for (int k2 = 0; k2 < 2; ++k2) {
;       _Pragma("unroll") for (int s2 = 0; s2 < 2; ++s2) {
;         bf16x8 pb = pack8(st[k2][8 * s2], st[k2][8 * s2 + 1], st[k2][8 * s2 + 2], st[k2][8 * s2 + 3],
;                           st[k2][8 * s2 + 4], st[k2][8 * s2 + 5], st[k2][8 * s2 + 6], st[k2][8 * s2 + 7]);
;         const int c0 = 4 * k2 + 2 * s2;
;         _Pragma("unroll") for (int mt = 0; mt < 4; ++mt) {
;           const char* vrow = sv + (32 * mt + r) * 128 + 8 * h;
;           s16x4 lo = *(const s16x4*)(vrow + ((c0 ^ rr8) << 4));
;           s16x4 hi = *(const s16x4*)(vrow + (((c0 + 1) ^ rr8) << 4));
;           bf16x8 va = __builtin_shufflevector(lo, hi, 0, 1, 2, 3, 4, 5, 6, 7);
;           o[mt] = MFMA32(va, pb, o[mt]);
;         }
;       }
;     }
;     cur = (cur == 2) ? 0 : cur + 1;
;   }
;   asm volatile("s_waitcnt vmcnt(0) lgkmcnt(0)" ::: "memory");
;   __syncthreads();
;   lrun += __shfl_xor(lrun, 32);
;   const float inv = 1.f / lrun;
;   _Pragma("unroll") for (int mt = 0; mt < 4; ++mt) {
;     _Pragma("unroll") for (int g = 0; g < 4; ++g) {
;       const int dv = 32 * mt + 8 * g + 4 * h;
;       const size_t off = (size_t)qrow * 1024 + head * 128 + dv;
;       u32x2 gv = *(const u32x2*)(P.gb + off);
;       u32x2 ov;
;       ov[0] = pack2(o[mt][4 * g] * inv * siluf_(bflo(gv[0])), o[mt][4 * g + 1] * inv * siluf_(bfhi(gv[0])));
;       ov[1] = pack2(o[mt][4 * g + 2] * inv * siluf_(bflo(gv[1])), o[mt][4 * g + 3] * inv * siluf_(bfhi(gv[1])));
;       *(u32x2*)(P.mo + off) = ov;
	v_mfma_f32_32x32x16_bf16 v[48:63], v[72:75], v[66:69], v[48:63]
	v_mfma_f32_32x32x16_bf16 v[32:47], v[76:79], v[66:69], v[32:47]
	v_add_u32_e32 v71, v205, v191
	v_add_u32_e32 v251, v205, v192
	ds_read_b64 v[72:73], v71 offset:24576
	ds_read_b64 v[74:75], v251 offset:24576
	ds_read_b64 v[76:77], v71 offset:28672
	ds_read_b64 v[78:79], v251 offset:28672
	v_add_f32_e32 v64, v90, v64
	v_add_f32_e32 v64, v212, v64
	s_waitcnt lgkmcnt(4)
	v_mfma_f32_32x32x16_bf16 v[16:31], v[252:255], v[66:69], v[16:31]
	v_mfma_f32_32x32x16_bf16 v[0:15], v[80:83], v[66:69], v[0:15]
	v_cvt_pk_bf16_f32 v66, v206, v65
	v_cvt_pk_bf16_f32 v67, v207, v208
	v_cvt_pk_bf16_f32 v68, v209, v85
	v_cvt_pk_bf16_f32 v69, v86, v87
	ds_read_b64 v[252:253], v71 offset:32768
	ds_read_b64 v[254:255], v251 offset:32768
	ds_read_b64 v[80:81], v71 offset:36864
	ds_read_b64 v[82:83], v251 offset:36864
	v_add_f32_e32 v64, v91, v64
	v_add_f32_e32 v64, v213, v64
	s_waitcnt lgkmcnt(4)
	v_mfma_f32_32x32x16_bf16 v[48:63], v[72:75], v[66:69], v[48:63]
	v_mfma_f32_32x32x16_bf16 v[32:47], v[76:79], v[66:69], v[32:47]
	v_add_u32_e32 v71, v205, v193
	v_add_u32_e32 v251, v205, v194
	ds_read_b64 v[72:73], v71 offset:24576
	ds_read_b64 v[74:75], v251 offset:24576
	ds_read_b64 v[76:77], v71 offset:28672
	ds_read_b64 v[78:79], v251 offset:28672
	v_add_f32_e32 v64, v92, v64
	v_add_f32_e32 v64, v214, v64
	s_waitcnt lgkmcnt(4)
	v_mfma_f32_32x32x16_bf16 v[16:31], v[252:255], v[66:69], v[16:31]
	v_mfma_f32_32x32x16_bf16 v[0:15], v[80:83], v[66:69], v[0:15]
	v_cvt_pk_bf16_f32 v66, v210, v211
	v_cvt_pk_bf16_f32 v67, v212, v213
	v_cvt_pk_bf16_f32 v68, v214, v215
	v_cvt_pk_bf16_f32 v69, v216, v217
	ds_read_b64 v[252:253], v71 offset:32768
	ds_read_b64 v[254:255], v251 offset:32768
	ds_read_b64 v[80:81], v71 offset:36864
	ds_read_b64 v[82:83], v251 offset:36864
	v_add_f32_e32 v64, v93, v64
	v_add_f32_e32 v64, v215, v64
	v_add_f32_e32 v64, v94, v64
	v_add_f32_e32 v64, v216, v64
	v_add_f32_e32 v64, v95, v64
	v_add_f32_e32 v64, v217, v64
	v_fmac_f32_e32 v64, v197, v196
	v_mov_b32_e32 v196, v195
	s_waitcnt lgkmcnt(4)
	v_mfma_f32_32x32x16_bf16 v[48:63], v[72:75], v[66:69], v[48:63]
	v_mfma_f32_32x32x16_bf16 v[32:47], v[76:79], v[66:69], v[32:47]
	s_waitcnt lgkmcnt(0)
	v_mfma_f32_32x32x16_bf16 v[16:31], v[252:255], v[66:69], v[16:31]
	v_mfma_f32_32x32x16_bf16 v[0:15], v[80:83], v[66:69], v[0:15]
	s_cbranch_scc1 .LBB0_729
	ds_bpermute_b32 v65, v152, v64
	v_readlane_b32 s12, v250, 10
	v_readlane_b32 s13, v250, 11
	s_waitcnt vmcnt(0) lgkmcnt(0)
	s_waitcnt vmcnt(0) lgkmcnt(0)
	v_add_f32_e32 v64, v64, v65
	v_div_scale_f32 v65, s[0:1], v64, v64, 1.0
	v_rcp_f32_e32 v66, v65
	s_barrier
	s_add_i32 s10, s10, s74
	v_fma_f32 v67, -v65, v66, 1.0
	v_fmac_f32_e32 v66, v67, v66
	v_div_scale_f32 v67, vcc, 1.0, v64, 1.0
	v_mul_f32_e32 v68, v67, v66
	v_fma_f32 v69, -v65, v68, v67
	v_fmac_f32_e32 v68, v69, v66
	v_fma_f32 v65, -v65, v68, v67
	v_div_fmas_f32 v65, v65, v66, v68
	v_div_fixup_f32 v64, v65, v64, 1.0
	v_lshlrev_b32_e32 v65, 2, v166
	v_lshlrev_b64 v[66:67], 10, v[154:155]
	v_or3_b32 v66, s11, v65, v66
	v_lshlrev_b64 v[68:69], 1, v[66:67]
	v_lshl_add_u64 v[70:71], s[12:13], 0, v[68:69]
	global_load_dwordx2 v[70:71], v[70:71], off
	v_readlane_b32 s18, v250, 16
	v_readlane_b32 s19, v250, 17
	v_readlane_b32 s20, v250, 18
	v_readlane_b32 s21, v250, 19
	v_readlane_b32 s22, v250, 20
	v_readlane_b32 s23, v250, 21
	s_cmpk_gt_i32 s10, 0x1ff
	v_readlane_b32 s14, v250, 12
	v_readlane_b32 s15, v250, 13
	v_readlane_b32 s16, v250, 14
	v_readlane_b32 s17, v250, 15
	v_readlane_b32 s24, v250, 22
	v_readlane_b32 s25, v250, 23
	v_readlane_b32 s26, v250, 24
	v_readlane_b32 s27, v250, 25
	s_waitcnt vmcnt(0)
	v_lshlrev_b32_e32 v72, 16, v70
	v_mul_f32_e32 v65, 0xbfb8aa3b, v72
	v_exp_f32_e32 v65, v65
	v_and_b32_e32 v73, 0xffff0000, v70
	v_lshlrev_b32_e32 v70, 16, v71
	v_and_b32_e32 v71, 0xffff0000, v71
	v_add_f32_e32 v65, 1.0, v65
	v_rcp_f32_e32 v74, v65
	v_pk_mul_f32 v[48:49], v[48:49], v[64:65] op_sel_hi:[1,0]
	v_mul_f32_e32 v65, 0xbfb8aa3b, v73
	v_exp_f32_e32 v65, v65
	s_nop 0
	v_add_f32_e32 v65, 1.0, v65
	v_rcp_f32_e32 v75, v65
	v_pk_mul_f32 v[50:51], v[50:51], v[64:65] op_sel_hi:[1,0]
	v_pk_mul_f32 v[52:53], v[52:53], v[64:65] op_sel_hi:[1,0]
	v_pk_mul_f32 v[54:55], v[54:55], v[64:65] op_sel_hi:[1,0]
	v_pk_mul_f32 v[72:73], v[74:75], v[72:73]
	v_pk_mul_f32 v[56:57], v[56:57], v[64:65] op_sel_hi:[1,0]
	v_pk_mul_f32 v[48:49], v[48:49], v[72:73]
	v_pk_mul_f32 v[32:33], v[32:33], v[64:65] op_sel_hi:[1,0]
	v_cvt_pk_bf16_f32 v48, v48, v49
	v_mul_f32_e32 v49, 0xbfb8aa3b, v70
	v_exp_f32_e32 v49, v49
	v_pk_mul_f32 v[34:35], v[34:35], v[64:65] op_sel_hi:[1,0]
	v_pk_mul_f32 v[36:37], v[36:37], v[64:65] op_sel_hi:[1,0]
	v_pk_mul_f32 v[38:39], v[38:39], v[64:65] op_sel_hi:[1,0]
	v_add_f32_e32 v49, 1.0, v49
	v_rcp_f32_e32 v72, v49
	v_mul_f32_e32 v49, 0xbfb8aa3b, v71
	v_exp_f32_e32 v49, v49
	v_pk_mul_f32 v[40:41], v[40:41], v[64:65] op_sel_hi:[1,0]
	v_pk_mul_f32 v[16:17], v[16:17], v[64:65] op_sel_hi:[1,0]
	v_pk_mul_f32 v[18:19], v[18:19], v[64:65] op_sel_hi:[1,0]
	v_add_f32_e32 v49, 1.0, v49
	v_rcp_f32_e32 v73, v49
	v_pk_mul_f32 v[20:21], v[20:21], v[64:65] op_sel_hi:[1,0]
	v_pk_mul_f32 v[22:23], v[22:23], v[64:65] op_sel_hi:[1,0]
	v_pk_mul_f32 v[24:25], v[24:25], v[64:65] op_sel_hi:[1,0]
	v_pk_mul_f32 v[70:71], v[72:73], v[70:71]
	v_pk_mul_f32 v[0:1], v[0:1], v[64:65] op_sel_hi:[1,0]
	v_pk_mul_f32 v[50:51], v[50:51], v[70:71]
	v_pk_mul_f32 v[2:3], v[2:3], v[64:65] op_sel_hi:[1,0]
	v_cvt_pk_bf16_f32 v49, v50, v51
	v_lshl_add_u64 v[50:51], s[58:59], 0, v[68:69]
	global_store_dwordx2 v[50:51], v[48:49], off
	v_or_b32_e32 v48, 8, v66
	v_mov_b32_e32 v49, v67
	v_lshlrev_b64 v[48:49], 1, v[48:49]
	v_lshl_add_u64 v[50:51], s[12:13], 0, v[48:49]
	global_load_dwordx2 v[50:51], v[50:51], off
	v_lshl_add_u64 v[48:49], s[58:59], 0, v[48:49]
	v_pk_mul_f32 v[4:5], v[4:5], v[64:65] op_sel_hi:[1,0]
	v_pk_mul_f32 v[6:7], v[6:7], v[64:65] op_sel_hi:[1,0]
	v_pk_mul_f32 v[8:9], v[8:9], v[64:65] op_sel_hi:[1,0]
	s_waitcnt vmcnt(0)
; DI unsigned pack2(float a, float b) { f32x2_t v = {a, b}; return __builtin_bit_cast(unsigned, __builtin_convertvector(v, bf16x2_t)); }
; DI float bflo(unsigned p) { return __uint_as_float(p << 16); }
; DI float bfhi(unsigned p) { return __uint_as_float(p & 0xffff0000u); }
; DI float siluf_(float x) { return x * frcp(1.f + __expf(-x)); }
; DI void attn_item(const Params& P, int half, int item, char* smem) {
;     ...
;   _Pragma("unroll") for (int mt = 0; mt < 4; ++mt) {
;     _Pragma("unroll") for (int g = 0; g < 4; ++g) {
;       const int dv = 32 * mt + 8 * g + 4 * h;
;       const size_t off = (size_t)qrow * 1024 + head * 128 + dv;
;       u32x2 gv = *(const u32x2*)(P.gb + off);
;       u32x2 ov;
;       ov[0] = pack2(o[mt][4 * g] * inv * siluf_(bflo(gv[0])), o[mt][4 * g + 1] * inv * siluf_(bfhi(gv[0])));
;       ov[1] = pack2(o[mt][4 * g + 2] * inv * siluf_(bflo(gv[1])), o[mt][4 * g + 3] * inv * siluf_(bfhi(gv[1])));
;       *(u32x2*)(P.mo + off) = ov;
;     }
;   }
	v_lshlrev_b32_e32 v68, 16, v50
	v_and_b32_e32 v69, 0xffff0000, v50
	v_mul_f32_e32 v50, 0xbfb8aa3b, v68
	v_exp_f32_e32 v50, v50
	s_nop 0
	v_add_f32_e32 v50, 1.0, v50
	v_rcp_f32_e32 v70, v50
	v_mul_f32_e32 v50, 0xbfb8aa3b, v69
	v_exp_f32_e32 v50, v50
	s_nop 0
	v_add_f32_e32 v50, 1.0, v50
	v_rcp_f32_e32 v71, v50
	s_nop 0
	v_pk_mul_f32 v[68:69], v[70:71], v[68:69]
	s_nop 0
	v_pk_mul_f32 v[52:53], v[52:53], v[68:69]
	s_nop 0
	v_cvt_pk_bf16_f32 v50, v52, v53
	v_lshlrev_b32_e32 v52, 16, v51
	v_and_b32_e32 v53, 0xffff0000, v51
	v_mul_f32_e32 v51, 0xbfb8aa3b, v52
	v_exp_f32_e32 v51, v51
	s_nop 0
	v_add_f32_e32 v51, 1.0, v51
	v_rcp_f32_e32 v68, v51
	v_mul_f32_e32 v51, 0xbfb8aa3b, v53
	v_exp_f32_e32 v51, v51
	s_nop 0
	v_add_f32_e32 v51, 1.0, v51
	v_rcp_f32_e32 v69, v51
	s_nop 0
	v_pk_mul_f32 v[52:53], v[68:69], v[52:53]
	s_nop 0
	v_pk_mul_f32 v[52:53], v[54:55], v[52:53]
	s_nop 0
	v_cvt_pk_bf16_f32 v51, v52, v53
	global_store_dwordx2 v[48:49], v[50:51], off
	v_or_b32_e32 v48, 16, v66
	v_mov_b32_e32 v49, v67
	v_lshlrev_b64 v[48:49], 1, v[48:49]
	v_lshl_add_u64 v[50:51], s[12:13], 0, v[48:49]
	global_load_dwordx2 v[50:51], v[50:51], off
	v_lshl_add_u64 v[48:49], s[58:59], 0, v[48:49]
	s_waitcnt vmcnt(0)
	v_lshlrev_b32_e32 v52, 16, v50
	v_and_b32_e32 v53, 0xffff0000, v50
	v_mul_f32_e32 v50, 0xbfb8aa3b, v52
	v_exp_f32_e32 v50, v50
	s_nop 0
	v_add_f32_e32 v50, 1.0, v50
	v_rcp_f32_e32 v54, v50
	v_mul_f32_e32 v50, 0xbfb8aa3b, v53
	v_exp_f32_e32 v50, v50
	s_nop 0
	v_add_f32_e32 v50, 1.0, v50
	v_rcp_f32_e32 v55, v50
	s_nop 0
	v_pk_mul_f32 v[52:53], v[54:55], v[52:53]
	s_nop 0
	v_pk_mul_f32 v[52:53], v[56:57], v[52:53]
	v_pk_mul_f32 v[56:57], v[58:59], v[64:65] op_sel_hi:[1,0]
	v_cvt_pk_bf16_f32 v50, v52, v53
	v_lshlrev_b32_e32 v52, 16, v51
	v_and_b32_e32 v53, 0xffff0000, v51
	v_mul_f32_e32 v51, 0xbfb8aa3b, v52
	v_exp_f32_e32 v51, v51
	s_nop 0
	v_add_f32_e32 v51, 1.0, v51
	v_rcp_f32_e32 v54, v51
	v_mul_f32_e32 v51, 0xbfb8aa3b, v53
	v_exp_f32_e32 v51, v51
	s_nop 0
	v_add_f32_e32 v51, 1.0, v51
	v_rcp_f32_e32 v55, v51
	s_nop 0
	v_pk_mul_f32 v[52:53], v[54:55], v[52:53]
	s_nop 0
	v_pk_mul_f32 v[52:53], v[56:57], v[52:53]
	v_pk_mul_f32 v[56:57], v[60:61], v[64:65] op_sel_hi:[1,0]
	v_cvt_pk_bf16_f32 v51, v52, v53
	global_store_dwordx2 v[48:49], v[50:51], off
	v_or_b32_e32 v48, 24, v66
	v_mov_b32_e32 v49, v67
	v_lshlrev_b64 v[48:49], 1, v[48:49]
	v_lshl_add_u64 v[50:51], s[12:13], 0, v[48:49]
	global_load_dwordx2 v[50:51], v[50:51], off
	v_lshl_add_u64 v[48:49], s[58:59], 0, v[48:49]
	s_waitcnt vmcnt(0)
	v_lshlrev_b32_e32 v52, 16, v50
	v_and_b32_e32 v53, 0xffff0000, v50
	v_mul_f32_e32 v50, 0xbfb8aa3b, v52
	v_exp_f32_e32 v50, v50
	s_nop 0
	v_add_f32_e32 v50, 1.0, v50
	v_rcp_f32_e32 v54, v50
	v_mul_f32_e32 v50, 0xbfb8aa3b, v53
	v_exp_f32_e32 v50, v50
	s_nop 0
	v_add_f32_e32 v50, 1.0, v50
	v_rcp_f32_e32 v55, v50
	s_nop 0
	v_pk_mul_f32 v[52:53], v[54:55], v[52:53]
	s_nop 0
	v_pk_mul_f32 v[52:53], v[56:57], v[52:53]
	v_pk_mul_f32 v[56:57], v[62:63], v[64:65] op_sel_hi:[1,0]
	v_cvt_pk_bf16_f32 v50, v52, v53
	v_lshlrev_b32_e32 v52, 16, v51
	v_and_b32_e32 v53, 0xffff0000, v51
	v_mul_f32_e32 v51, 0xbfb8aa3b, v52
	v_exp_f32_e32 v51, v51
	s_nop 0
	v_add_f32_e32 v51, 1.0, v51
	v_rcp_f32_e32 v54, v51
	v_mul_f32_e32 v51, 0xbfb8aa3b, v53
	v_exp_f32_e32 v51, v51
	s_nop 0
	v_add_f32_e32 v51, 1.0, v51
	v_rcp_f32_e32 v55, v51
	s_nop 0
	v_pk_mul_f32 v[52:53], v[54:55], v[52:53]
	s_nop 0
	v_pk_mul_f32 v[52:53], v[56:57], v[52:53]
	s_nop 0
	v_cvt_pk_bf16_f32 v51, v52, v53
	global_store_dwordx2 v[48:49], v[50:51], off
	v_or_b32_e32 v48, 32, v66
	v_mov_b32_e32 v49, v67
	v_lshlrev_b64 v[48:49], 1, v[48:49]
	v_lshl_add_u64 v[50:51], s[12:13], 0, v[48:49]
	global_load_dwordx2 v[50:51], v[50:51], off
	s_waitcnt vmcnt(0)
	v_lshlrev_b32_e32 v52, 16, v50
	v_and_b32_e32 v53, 0xffff0000, v50
	v_mul_f32_e32 v50, 0xbfb8aa3b, v52
	v_exp_f32_e32 v50, v50
	s_nop 0
	v_add_f32_e32 v50, 1.0, v50
	v_rcp_f32_e32 v54, v50
	v_mul_f32_e32 v50, 0xbfb8aa3b, v53
	v_exp_f32_e32 v50, v50
	s_nop 0
	v_add_f32_e32 v50, 1.0, v50
	v_rcp_f32_e32 v55, v50
	v_lshlrev_b32_e32 v50, 16, v51
	v_and_b32_e32 v51, 0xffff0000, v51
	v_pk_mul_f32 v[52:53], v[54:55], v[52:53]
	s_nop 0
	v_pk_mul_f32 v[32:33], v[32:33], v[52:53]
	s_nop 0
	v_cvt_pk_bf16_f32 v32, v32, v33
	v_mul_f32_e32 v33, 0xbfb8aa3b, v50
	v_exp_f32_e32 v33, v33
	s_nop 0
	v_add_f32_e32 v33, 1.0, v33
	v_rcp_f32_e32 v52, v33
	v_mul_f32_e32 v33, 0xbfb8aa3b, v51
	v_exp_f32_e32 v33, v33
	s_nop 0
	v_add_f32_e32 v33, 1.0, v33
	v_rcp_f32_e32 v53, v33
	s_nop 0
	v_pk_mul_f32 v[50:51], v[52:53], v[50:51]
	s_nop 0
	v_pk_mul_f32 v[34:35], v[34:35], v[50:51]
	s_nop 0
	v_cvt_pk_bf16_f32 v33, v34, v35
	v_lshl_add_u64 v[34:35], s[58:59], 0, v[48:49]
	global_store_dwordx2 v[34:35], v[32:33], off
	v_or_b32_e32 v32, 40, v66
	v_mov_b32_e32 v33, v67
	v_lshlrev_b64 v[32:33], 1, v[32:33]
	v_lshl_add_u64 v[34:35], s[12:13], 0, v[32:33]
	global_load_dwordx2 v[34:35], v[34:35], off
	v_lshl_add_u64 v[32:33], s[58:59], 0, v[32:33]
	s_waitcnt vmcnt(0)
	v_lshlrev_b32_e32 v48, 16, v34
	v_and_b32_e32 v49, 0xffff0000, v34
	v_mul_f32_e32 v34, 0xbfb8aa3b, v48
	v_exp_f32_e32 v34, v34
	s_nop 0
	v_add_f32_e32 v34, 1.0, v34
	v_rcp_f32_e32 v50, v34
	v_mul_f32_e32 v34, 0xbfb8aa3b, v49
	v_exp_f32_e32 v34, v34
	s_nop 0
	v_add_f32_e32 v34, 1.0, v34
	v_rcp_f32_e32 v51, v34
	s_nop 0
	v_pk_mul_f32 v[48:49], v[50:51], v[48:49]
	s_nop 0
	v_pk_mul_f32 v[36:37], v[36:37], v[48:49]
	s_nop 0
	v_cvt_pk_bf16_f32 v34, v36, v37
	v_lshlrev_b32_e32 v36, 16, v35
	v_and_b32_e32 v37, 0xffff0000, v35
	v_mul_f32_e32 v35, 0xbfb8aa3b, v36
	v_exp_f32_e32 v35, v35
	s_nop 0
	v_add_f32_e32 v35, 1.0, v35
	v_rcp_f32_e32 v48, v35
	v_mul_f32_e32 v35, 0xbfb8aa3b, v37
	v_exp_f32_e32 v35, v35
	s_nop 0
	v_add_f32_e32 v35, 1.0, v35
	v_rcp_f32_e32 v49, v35
	s_nop 0
	v_pk_mul_f32 v[36:37], v[48:49], v[36:37]
	s_nop 0
	v_pk_mul_f32 v[36:37], v[38:39], v[36:37]
	s_nop 0
	v_cvt_pk_bf16_f32 v35, v36, v37
	global_store_dwordx2 v[32:33], v[34:35], off
	v_or_b32_e32 v32, 48, v66
	v_mov_b32_e32 v33, v67
	v_lshlrev_b64 v[32:33], 1, v[32:33]
	v_lshl_add_u64 v[34:35], s[12:13], 0, v[32:33]
	global_load_dwordx2 v[34:35], v[34:35], off
	v_lshl_add_u64 v[32:33], s[58:59], 0, v[32:33]
	s_waitcnt vmcnt(0)
; DI unsigned pack2(float a, float b) { f32x2_t v = {a, b}; return __builtin_bit_cast(unsigned, __builtin_convertvector(v, bf16x2_t)); }
; DI float bflo(unsigned p) { return __uint_as_float(p << 16); }
; DI float bfhi(unsigned p) { return __uint_as_float(p & 0xffff0000u); }
; DI float siluf_(float x) { return x * frcp(1.f + __expf(-x)); }
; DI void attn_item(const Params& P, int half, int item, char* smem) {
;     ...
;   _Pragma("unroll") for (int mt = 0; mt < 4; ++mt) {
;     _Pragma("unroll") for (int g = 0; g < 4; ++g) {
;       const int dv = 32 * mt + 8 * g + 4 * h;
;       const size_t off = (size_t)qrow * 1024 + head * 128 + dv;
;       u32x2 gv = *(const u32x2*)(P.gb + off);
;       u32x2 ov;
;       ov[0] = pack2(o[mt][4 * g] * inv * siluf_(bflo(gv[0])), o[mt][4 * g + 1] * inv * siluf_(bfhi(gv[0])));
;       ov[1] = pack2(o[mt][4 * g + 2] * inv * siluf_(bflo(gv[1])), o[mt][4 * g + 3] * inv * siluf_(bfhi(gv[1])));
;       *(u32x2*)(P.mo + off) = ov;
;     }
;   }
	v_lshlrev_b32_e32 v36, 16, v34
	v_and_b32_e32 v37, 0xffff0000, v34
	v_mul_f32_e32 v34, 0xbfb8aa3b, v36
	v_exp_f32_e32 v34, v34
	s_nop 0
	v_add_f32_e32 v34, 1.0, v34
	v_rcp_f32_e32 v38, v34
	v_mul_f32_e32 v34, 0xbfb8aa3b, v37
	v_exp_f32_e32 v34, v34
	s_nop 0
	v_add_f32_e32 v34, 1.0, v34
	v_rcp_f32_e32 v39, v34
	s_nop 0
	v_pk_mul_f32 v[36:37], v[38:39], v[36:37]
	s_nop 0
	v_pk_mul_f32 v[36:37], v[40:41], v[36:37]
	v_pk_mul_f32 v[40:41], v[42:43], v[64:65] op_sel_hi:[1,0]
	v_cvt_pk_bf16_f32 v34, v36, v37
	v_lshlrev_b32_e32 v36, 16, v35
	v_and_b32_e32 v37, 0xffff0000, v35
	v_mul_f32_e32 v35, 0xbfb8aa3b, v36
	v_exp_f32_e32 v35, v35
	s_nop 0
	v_add_f32_e32 v35, 1.0, v35
	v_rcp_f32_e32 v38, v35
	v_mul_f32_e32 v35, 0xbfb8aa3b, v37
	v_exp_f32_e32 v35, v35
	s_nop 0
	v_add_f32_e32 v35, 1.0, v35
	v_rcp_f32_e32 v39, v35
	s_nop 0
	v_pk_mul_f32 v[36:37], v[38:39], v[36:37]
	s_nop 0
	v_pk_mul_f32 v[36:37], v[40:41], v[36:37]
	v_pk_mul_f32 v[40:41], v[44:45], v[64:65] op_sel_hi:[1,0]
	v_cvt_pk_bf16_f32 v35, v36, v37
	global_store_dwordx2 v[32:33], v[34:35], off
	v_or_b32_e32 v32, 56, v66
	v_mov_b32_e32 v33, v67
	v_lshlrev_b64 v[32:33], 1, v[32:33]
	v_lshl_add_u64 v[34:35], s[12:13], 0, v[32:33]
	global_load_dwordx2 v[34:35], v[34:35], off
	v_lshl_add_u64 v[32:33], s[58:59], 0, v[32:33]
	s_waitcnt vmcnt(0)
	v_lshlrev_b32_e32 v36, 16, v34
	v_and_b32_e32 v37, 0xffff0000, v34
	v_mul_f32_e32 v34, 0xbfb8aa3b, v36
	v_exp_f32_e32 v34, v34
	s_nop 0
	v_add_f32_e32 v34, 1.0, v34
	v_rcp_f32_e32 v38, v34
	v_mul_f32_e32 v34, 0xbfb8aa3b, v37
	v_exp_f32_e32 v34, v34
	s_nop 0
	v_add_f32_e32 v34, 1.0, v34
	v_rcp_f32_e32 v39, v34
	s_nop 0
	v_pk_mul_f32 v[36:37], v[38:39], v[36:37]
	s_nop 0
	v_pk_mul_f32 v[36:37], v[40:41], v[36:37]
	v_pk_mul_f32 v[40:41], v[46:47], v[64:65] op_sel_hi:[1,0]
	v_cvt_pk_bf16_f32 v34, v36, v37
	v_lshlrev_b32_e32 v36, 16, v35
	v_and_b32_e32 v37, 0xffff0000, v35
	v_mul_f32_e32 v35, 0xbfb8aa3b, v36
	v_exp_f32_e32 v35, v35
	s_nop 0
	v_add_f32_e32 v35, 1.0, v35
	v_rcp_f32_e32 v38, v35
	v_mul_f32_e32 v35, 0xbfb8aa3b, v37
	v_exp_f32_e32 v35, v35
	s_nop 0
	v_add_f32_e32 v35, 1.0, v35
	v_rcp_f32_e32 v39, v35
	s_nop 0
	v_pk_mul_f32 v[36:37], v[38:39], v[36:37]
	s_nop 0
	v_pk_mul_f32 v[36:37], v[40:41], v[36:37]
	s_nop 0
	v_cvt_pk_bf16_f32 v35, v36, v37
	global_store_dwordx2 v[32:33], v[34:35], off
	v_or_b32_e32 v32, 64, v66
	v_mov_b32_e32 v33, v67
	v_lshlrev_b64 v[32:33], 1, v[32:33]
	v_lshl_add_u64 v[34:35], s[12:13], 0, v[32:33]
	global_load_dwordx2 v[34:35], v[34:35], off
	s_waitcnt vmcnt(0)
	v_lshlrev_b32_e32 v36, 16, v34
	v_and_b32_e32 v37, 0xffff0000, v34
	v_mul_f32_e32 v34, 0xbfb8aa3b, v36
	v_exp_f32_e32 v34, v34
	s_nop 0
	v_add_f32_e32 v34, 1.0, v34
	v_rcp_f32_e32 v38, v34
	v_mul_f32_e32 v34, 0xbfb8aa3b, v37
	v_exp_f32_e32 v34, v34
	s_nop 0
	v_add_f32_e32 v34, 1.0, v34
	v_rcp_f32_e32 v39, v34
	v_lshlrev_b32_e32 v34, 16, v35
	v_and_b32_e32 v35, 0xffff0000, v35
	v_pk_mul_f32 v[36:37], v[38:39], v[36:37]
	s_nop 0
	v_pk_mul_f32 v[16:17], v[16:17], v[36:37]
	s_nop 0
	v_cvt_pk_bf16_f32 v16, v16, v17
	v_mul_f32_e32 v17, 0xbfb8aa3b, v34
	v_exp_f32_e32 v17, v17
	s_nop 0
	v_add_f32_e32 v17, 1.0, v17
	v_rcp_f32_e32 v36, v17
	v_mul_f32_e32 v17, 0xbfb8aa3b, v35
	v_exp_f32_e32 v17, v17
	s_nop 0
	v_add_f32_e32 v17, 1.0, v17
	v_rcp_f32_e32 v37, v17
	s_nop 0
	v_pk_mul_f32 v[34:35], v[36:37], v[34:35]
	s_nop 0
	v_pk_mul_f32 v[18:19], v[18:19], v[34:35]
	s_nop 0
	v_cvt_pk_bf16_f32 v17, v18, v19
	v_lshl_add_u64 v[18:19], s[58:59], 0, v[32:33]
	global_store_dwordx2 v[18:19], v[16:17], off
	v_or_b32_e32 v16, 0x48, v66
	v_mov_b32_e32 v17, v67
	v_lshlrev_b64 v[16:17], 1, v[16:17]
	v_lshl_add_u64 v[18:19], s[12:13], 0, v[16:17]
	global_load_dwordx2 v[18:19], v[18:19], off
	v_lshl_add_u64 v[16:17], s[58:59], 0, v[16:17]
	s_waitcnt vmcnt(0)
	v_lshlrev_b32_e32 v32, 16, v18
	v_and_b32_e32 v33, 0xffff0000, v18
	v_mul_f32_e32 v18, 0xbfb8aa3b, v32
	v_exp_f32_e32 v18, v18
	s_nop 0
	v_add_f32_e32 v18, 1.0, v18
	v_rcp_f32_e32 v34, v18
	v_mul_f32_e32 v18, 0xbfb8aa3b, v33
	v_exp_f32_e32 v18, v18
	s_nop 0
	v_add_f32_e32 v18, 1.0, v18
	v_rcp_f32_e32 v35, v18
	s_nop 0
	v_pk_mul_f32 v[32:33], v[34:35], v[32:33]
	s_nop 0
	v_pk_mul_f32 v[20:21], v[20:21], v[32:33]
	s_nop 0
	v_cvt_pk_bf16_f32 v18, v20, v21
	v_lshlrev_b32_e32 v20, 16, v19
	v_and_b32_e32 v21, 0xffff0000, v19
	v_mul_f32_e32 v19, 0xbfb8aa3b, v20
	v_exp_f32_e32 v19, v19
	s_nop 0
	v_add_f32_e32 v19, 1.0, v19
	v_rcp_f32_e32 v32, v19
	v_mul_f32_e32 v19, 0xbfb8aa3b, v21
	v_exp_f32_e32 v19, v19
	s_nop 0
	v_add_f32_e32 v19, 1.0, v19
	v_rcp_f32_e32 v33, v19
	s_nop 0
	v_pk_mul_f32 v[20:21], v[32:33], v[20:21]
	s_nop 0
	v_pk_mul_f32 v[20:21], v[22:23], v[20:21]
	s_nop 0
	v_cvt_pk_bf16_f32 v19, v20, v21
	global_store_dwordx2 v[16:17], v[18:19], off
	v_or_b32_e32 v16, 0x50, v66
	v_mov_b32_e32 v17, v67
	v_lshlrev_b64 v[16:17], 1, v[16:17]
	v_lshl_add_u64 v[18:19], s[12:13], 0, v[16:17]
	global_load_dwordx2 v[18:19], v[18:19], off
	v_lshl_add_u64 v[16:17], s[58:59], 0, v[16:17]
	s_waitcnt vmcnt(0)
; DI unsigned pack2(float a, float b) { f32x2_t v = {a, b}; return __builtin_bit_cast(unsigned, __builtin_convertvector(v, bf16x2_t)); }
; DI float bflo(unsigned p) { return __uint_as_float(p << 16); }
; DI float bfhi(unsigned p) { return __uint_as_float(p & 0xffff0000u); }
; DI float siluf_(float x) { return x * frcp(1.f + __expf(-x)); }
; DI void attn_item(const Params& P, int half, int item, char* smem) {
;     ...
;   _Pragma("unroll") for (int mt = 0; mt < 4; ++mt) {
;     _Pragma("unroll") for (int g = 0; g < 4; ++g) {
;       const int dv = 32 * mt + 8 * g + 4 * h;
;       const size_t off = (size_t)qrow * 1024 + head * 128 + dv;
;       u32x2 gv = *(const u32x2*)(P.gb + off);
;       u32x2 ov;
;       ov[0] = pack2(o[mt][4 * g] * inv * siluf_(bflo(gv[0])), o[mt][4 * g + 1] * inv * siluf_(bfhi(gv[0])));
;       ov[1] = pack2(o[mt][4 * g + 2] * inv * siluf_(bflo(gv[1])), o[mt][4 * g + 3] * inv * siluf_(bfhi(gv[1])));
;       *(u32x2*)(P.mo + off) = ov;
;     }
;   }
	v_lshlrev_b32_e32 v20, 16, v18
	v_and_b32_e32 v21, 0xffff0000, v18
	v_mul_f32_e32 v18, 0xbfb8aa3b, v20
	v_exp_f32_e32 v18, v18
	s_nop 0
	v_add_f32_e32 v18, 1.0, v18
	v_rcp_f32_e32 v22, v18
	v_mul_f32_e32 v18, 0xbfb8aa3b, v21
	v_exp_f32_e32 v18, v18
	s_nop 0
	v_add_f32_e32 v18, 1.0, v18
	v_rcp_f32_e32 v23, v18
	s_nop 0
	v_pk_mul_f32 v[20:21], v[22:23], v[20:21]
	s_nop 0
	v_pk_mul_f32 v[20:21], v[24:25], v[20:21]
	v_pk_mul_f32 v[24:25], v[26:27], v[64:65] op_sel_hi:[1,0]
	v_cvt_pk_bf16_f32 v18, v20, v21
	v_lshlrev_b32_e32 v20, 16, v19
	v_and_b32_e32 v21, 0xffff0000, v19
	v_mul_f32_e32 v19, 0xbfb8aa3b, v20
	v_exp_f32_e32 v19, v19
	s_nop 0
	v_add_f32_e32 v19, 1.0, v19
	v_rcp_f32_e32 v22, v19
	v_mul_f32_e32 v19, 0xbfb8aa3b, v21
	v_exp_f32_e32 v19, v19
	s_nop 0
	v_add_f32_e32 v19, 1.0, v19
	v_rcp_f32_e32 v23, v19
	s_nop 0
	v_pk_mul_f32 v[20:21], v[22:23], v[20:21]
	s_nop 0
	v_pk_mul_f32 v[20:21], v[24:25], v[20:21]
	v_pk_mul_f32 v[24:25], v[28:29], v[64:65] op_sel_hi:[1,0]
	v_cvt_pk_bf16_f32 v19, v20, v21
	global_store_dwordx2 v[16:17], v[18:19], off
	v_or_b32_e32 v16, 0x58, v66
	v_mov_b32_e32 v17, v67
	v_lshlrev_b64 v[16:17], 1, v[16:17]
	v_lshl_add_u64 v[18:19], s[12:13], 0, v[16:17]
	global_load_dwordx2 v[18:19], v[18:19], off
	v_lshl_add_u64 v[16:17], s[58:59], 0, v[16:17]
	s_waitcnt vmcnt(0)
	v_lshlrev_b32_e32 v20, 16, v18
	v_and_b32_e32 v21, 0xffff0000, v18
	v_mul_f32_e32 v18, 0xbfb8aa3b, v20
	v_exp_f32_e32 v18, v18
	s_nop 0
	v_add_f32_e32 v18, 1.0, v18
	v_rcp_f32_e32 v22, v18
	v_mul_f32_e32 v18, 0xbfb8aa3b, v21
	v_exp_f32_e32 v18, v18
	s_nop 0
	v_add_f32_e32 v18, 1.0, v18
	v_rcp_f32_e32 v23, v18
	s_nop 0
	v_pk_mul_f32 v[20:21], v[22:23], v[20:21]
	s_nop 0
	v_pk_mul_f32 v[20:21], v[24:25], v[20:21]
	v_pk_mul_f32 v[24:25], v[30:31], v[64:65] op_sel_hi:[1,0]
	v_cvt_pk_bf16_f32 v18, v20, v21
	v_lshlrev_b32_e32 v20, 16, v19
	v_and_b32_e32 v21, 0xffff0000, v19
	v_mul_f32_e32 v19, 0xbfb8aa3b, v20
	v_exp_f32_e32 v19, v19
	s_nop 0
	v_add_f32_e32 v19, 1.0, v19
	v_rcp_f32_e32 v22, v19
	v_mul_f32_e32 v19, 0xbfb8aa3b, v21
	v_exp_f32_e32 v19, v19
	s_nop 0
	v_add_f32_e32 v19, 1.0, v19
	v_rcp_f32_e32 v23, v19
	s_nop 0
	v_pk_mul_f32 v[20:21], v[22:23], v[20:21]
	s_nop 0
	v_pk_mul_f32 v[20:21], v[24:25], v[20:21]
	s_nop 0
	v_cvt_pk_bf16_f32 v19, v20, v21
	global_store_dwordx2 v[16:17], v[18:19], off
	v_or_b32_e32 v16, 0x60, v66
	v_mov_b32_e32 v17, v67
	v_lshlrev_b64 v[16:17], 1, v[16:17]
	v_lshl_add_u64 v[18:19], s[12:13], 0, v[16:17]
	global_load_dwordx2 v[18:19], v[18:19], off
	s_waitcnt vmcnt(0)
	v_lshlrev_b32_e32 v20, 16, v18
	v_and_b32_e32 v21, 0xffff0000, v18
	v_mul_f32_e32 v18, 0xbfb8aa3b, v20
	v_exp_f32_e32 v18, v18
	s_nop 0
	v_add_f32_e32 v18, 1.0, v18
	v_rcp_f32_e32 v22, v18
	v_mul_f32_e32 v18, 0xbfb8aa3b, v21
	v_exp_f32_e32 v18, v18
	s_nop 0
	v_add_f32_e32 v18, 1.0, v18
	v_rcp_f32_e32 v23, v18
	v_lshlrev_b32_e32 v18, 16, v19
	v_and_b32_e32 v19, 0xffff0000, v19
	v_pk_mul_f32 v[20:21], v[22:23], v[20:21]
	s_nop 0
	v_pk_mul_f32 v[0:1], v[0:1], v[20:21]
	s_nop 0
	v_cvt_pk_bf16_f32 v0, v0, v1
	v_mul_f32_e32 v1, 0xbfb8aa3b, v18
	v_exp_f32_e32 v1, v1
	s_nop 0
	v_add_f32_e32 v1, 1.0, v1
	v_rcp_f32_e32 v20, v1
	v_mul_f32_e32 v1, 0xbfb8aa3b, v19
	v_exp_f32_e32 v1, v1
	s_nop 0
	v_add_f32_e32 v1, 1.0, v1
	v_rcp_f32_e32 v21, v1
	s_nop 0
	v_pk_mul_f32 v[18:19], v[20:21], v[18:19]
	s_nop 0
	v_pk_mul_f32 v[2:3], v[2:3], v[18:19]
	s_nop 0
	v_cvt_pk_bf16_f32 v1, v2, v3
	v_lshl_add_u64 v[2:3], s[58:59], 0, v[16:17]
	global_store_dwordx2 v[2:3], v[0:1], off
	v_or_b32_e32 v0, 0x68, v66
	v_mov_b32_e32 v1, v67
	v_lshlrev_b64 v[0:1], 1, v[0:1]
	v_lshl_add_u64 v[2:3], s[12:13], 0, v[0:1]
	global_load_dwordx2 v[2:3], v[2:3], off
	v_lshl_add_u64 v[0:1], s[58:59], 0, v[0:1]
	s_waitcnt vmcnt(0)
	v_lshlrev_b32_e32 v16, 16, v2
	v_and_b32_e32 v17, 0xffff0000, v2
	v_mul_f32_e32 v2, 0xbfb8aa3b, v16
	v_exp_f32_e32 v2, v2
	s_nop 0
	v_add_f32_e32 v2, 1.0, v2
	v_rcp_f32_e32 v18, v2
	v_mul_f32_e32 v2, 0xbfb8aa3b, v17
	v_exp_f32_e32 v2, v2
	s_nop 0
	v_add_f32_e32 v2, 1.0, v2
	v_rcp_f32_e32 v19, v2
	s_nop 0
	v_pk_mul_f32 v[16:17], v[18:19], v[16:17]
	s_nop 0
	v_pk_mul_f32 v[4:5], v[4:5], v[16:17]
	s_nop 0
	v_cvt_pk_bf16_f32 v2, v4, v5
	v_lshlrev_b32_e32 v4, 16, v3
	v_and_b32_e32 v5, 0xffff0000, v3
	v_mul_f32_e32 v3, 0xbfb8aa3b, v4
	v_exp_f32_e32 v3, v3
	s_nop 0
	v_add_f32_e32 v3, 1.0, v3
	v_rcp_f32_e32 v16, v3
	v_mul_f32_e32 v3, 0xbfb8aa3b, v5
	v_exp_f32_e32 v3, v3
	s_nop 0
	v_add_f32_e32 v3, 1.0, v3
	v_rcp_f32_e32 v17, v3
	s_nop 0
	v_pk_mul_f32 v[4:5], v[16:17], v[4:5]
	s_nop 0
	v_pk_mul_f32 v[4:5], v[6:7], v[4:5]
	s_nop 0
	v_cvt_pk_bf16_f32 v3, v4, v5
	global_store_dwordx2 v[0:1], v[2:3], off
	v_or_b32_e32 v0, 0x70, v66
	v_mov_b32_e32 v1, v67
	v_lshlrev_b64 v[0:1], 1, v[0:1]
	v_lshl_add_u64 v[2:3], s[12:13], 0, v[0:1]
	global_load_dwordx2 v[2:3], v[2:3], off
	v_lshl_add_u64 v[0:1], s[58:59], 0, v[0:1]
	v_or_b32_e32 v66, 0x78, v66
	s_waitcnt vmcnt(0)
	v_lshlrev_b32_e32 v4, 16, v2
	v_and_b32_e32 v5, 0xffff0000, v2
	v_mul_f32_e32 v2, 0xbfb8aa3b, v4
	v_exp_f32_e32 v2, v2
	s_nop 0
	v_add_f32_e32 v2, 1.0, v2
	v_rcp_f32_e32 v6, v2
	v_mul_f32_e32 v2, 0xbfb8aa3b, v5
	v_exp_f32_e32 v2, v2
	s_nop 0
	v_add_f32_e32 v2, 1.0, v2
	v_rcp_f32_e32 v7, v2
	s_nop 0
	v_pk_mul_f32 v[4:5], v[6:7], v[4:5]
	s_nop 0
	v_pk_mul_f32 v[4:5], v[8:9], v[4:5]
	v_pk_mul_f32 v[8:9], v[10:11], v[64:65] op_sel_hi:[1,0]
	v_cvt_pk_bf16_f32 v2, v4, v5
	v_lshlrev_b32_e32 v4, 16, v3
	v_and_b32_e32 v5, 0xffff0000, v3
	v_mul_f32_e32 v3, 0xbfb8aa3b, v4
	v_exp_f32_e32 v3, v3
	s_nop 0
	v_add_f32_e32 v3, 1.0, v3
	v_rcp_f32_e32 v6, v3
	v_mul_f32_e32 v3, 0xbfb8aa3b, v5
	v_exp_f32_e32 v3, v3
	s_nop 0
	v_add_f32_e32 v3, 1.0, v3
	v_rcp_f32_e32 v7, v3
	s_nop 0
	v_pk_mul_f32 v[4:5], v[6:7], v[4:5]
	s_nop 0
	v_pk_mul_f32 v[4:5], v[8:9], v[4:5]
	v_pk_mul_f32 v[8:9], v[12:13], v[64:65] op_sel_hi:[1,0]
	v_cvt_pk_bf16_f32 v3, v4, v5
	global_store_dwordx2 v[0:1], v[2:3], off
	v_lshlrev_b64 v[0:1], 1, v[66:67]
	v_lshl_add_u64 v[2:3], s[12:13], 0, v[0:1]
	global_load_dwordx2 v[2:3], v[2:3], off
	v_lshl_add_u64 v[0:1], s[58:59], 0, v[0:1]
	s_waitcnt vmcnt(0)
	v_lshlrev_b32_e32 v4, 16, v2
	v_and_b32_e32 v5, 0xffff0000, v2
	v_mul_f32_e32 v2, 0xbfb8aa3b, v4
	v_exp_f32_e32 v2, v2
	s_nop 0
	v_add_f32_e32 v2, 1.0, v2
	v_rcp_f32_e32 v6, v2
	v_mul_f32_e32 v2, 0xbfb8aa3b, v5
	v_exp_f32_e32 v2, v2
	s_nop 0
	v_add_f32_e32 v2, 1.0, v2
	v_rcp_f32_e32 v7, v2
	s_nop 0
	v_pk_mul_f32 v[4:5], v[6:7], v[4:5]
	s_nop 0
	v_pk_mul_f32 v[4:5], v[8:9], v[4:5]
	v_pk_mul_f32 v[8:9], v[14:15], v[64:65] op_sel_hi:[1,0]
	v_cvt_pk_bf16_f32 v2, v4, v5
	v_lshlrev_b32_e32 v4, 16, v3
	v_and_b32_e32 v5, 0xffff0000, v3
	v_mul_f32_e32 v3, 0xbfb8aa3b, v4
	v_exp_f32_e32 v3, v3
	s_nop 0
	v_add_f32_e32 v3, 1.0, v3
	v_rcp_f32_e32 v6, v3
	v_mul_f32_e32 v3, 0xbfb8aa3b, v5
	v_exp_f32_e32 v3, v3
	s_nop 0
	v_add_f32_e32 v3, 1.0, v3
	v_rcp_f32_e32 v7, v3
	s_nop 0
	v_pk_mul_f32 v[4:5], v[6:7], v[4:5]
	s_nop 0
	v_pk_mul_f32 v[4:5], v[8:9], v[4:5]
	s_nop 0
	v_cvt_pk_bf16_f32 v3, v4, v5
	global_store_dwordx2 v[0:1], v[2:3], off
	s_cbranch_scc0 .LBB0_728

; #define MFMA32(a, b, c) __builtin_amdgcn_mfma_f32_32x32x16_bf16((a), (b), (c), 0, 0, 0)
; DI float bflo(unsigned p) { return __uint_as_float(p << 16); }
; DI float bfhi(unsigned p) { return __uint_as_float(p & 0xffff0000u); }
; DI void hgrn_out(const Params& P, int l, int item, char* smem) {
;     ...
;     _Pragma("unroll 2") for (int ks = 0; ks < 8; ++ks) {
;       const int dk0 = 16 * ks + 8 * h;
;       u32x4 qraw = *(const u32x4*)(P.hq + (size_t)(t0 + t) * 1024 + head * 128 + dk0);
;       float4 bt0 = *(const float4*)(bs + t * BST + dk0), bt1 = *(const float4*)(bs + t * BST + dk0 + 4);
;       float4 rf0 = *(const float4*)(bs + 32 * BST + dk0), rf1 = *(const float4*)(bs + 32 * BST + dk0 + 4);
;       float q0 = bflo(qraw[0]), q1 = bfhi(qraw[0]), q2 = bflo(qraw[1]), q3 = bfhi(qraw[1]);
;       float q4 = bflo(qraw[2]), q5 = bfhi(qraw[2]), q6 = bflo(qraw[3]), q7 = bfhi(qraw[3]);
;       bf16x8 qref = pack8(q0 * __expf(bt0.x - rf0.x), q1 * __expf(bt0.y - rf0.y), q2 * __expf(bt0.z - rf0.z), q3 * __expf(bt0.w - rf0.w),
;                           q4 * __expf(bt1.x - rf1.x), q5 * __expf(bt1.y - rf1.y), q6 * __expf(bt1.z - rf1.z), q7 * __expf(bt1.w - rf1.w));
;       bf16x8 qint = pack8(q0 * __expf(bt0.x), q1 * __expf(bt0.y), q2 * __expf(bt0.z), q3 * __expf(bt0.w),
;                           q4 * __expf(bt1.x), q5 * __expf(bt1.y), q6 * __expf(bt1.z), q7 * __expf(bt1.w));
;       _Pragma("unroll") for (int st = 0; st < 2; ++st) {
;         const int s_ = 32 * st + r;
;         u32x4 kraw = *(const u32x4*)(kk + (size_t)(t0 + s_) * 1024 + head * 128 + dk0);
;         float4 b0 = *(const float4*)(bs + s_ * BST + dk0), b1 = *(const float4*)(bs + s_ * BST + dk0 + 4);
;         bf16x8 kt = pack8(bflo(kraw[0]) * __expf(rf0.x - b0.x), bfhi(kraw[0]) * __expf(rf0.y - b0.y),
;                           bflo(kraw[1]) * __expf(rf0.z - b0.z), bfhi(kraw[1]) * __expf(rf0.w - b0.w),
;                           bflo(kraw[2]) * __expf(rf1.x - b1.x), bfhi(kraw[2]) * __expf(rf1.y - b1.y),
;                           bflo(kraw[3]) * __expf(rf1.z - b1.z), bfhi(kraw[3]) * __expf(rf1.w - b1.w));
;         sc[st] = MFMA32(kt, qref, sc[st]);
;       }
.LBB0_743:
	v_lshl_add_u64 v[226:227], v[116:117], 0, s[76:77]
	v_lshl_add_u64 v[230:231], v[122:123], 0, s[76:77]
	v_lshl_add_u64 v[234:235], v[120:121], 0, s[76:77]
	v_lshl_add_u64 v[238:239], v[118:119], 0, s[76:77]
	global_load_dwordx4 v[206:209], v[226:227], off
	global_load_dwordx4 v[210:213], v[230:231], off
	global_load_dwordx4 v[214:217], v[234:235], off
	global_load_dwordx4 v[218:221], v[238:239], off
	v_add_co_u32_e32 v242, vcc, s33, v238
	s_nop 1
	v_addc_co_u32_e32 v243, vcc, 0, v239, vcc
	global_load_dwordx4 v[222:225], v[242:243], off
	global_load_dwordx4 v[226:229], v[226:227], off offset:32
	global_load_dwordx4 v[230:233], v[230:231], off offset:32
	global_load_dwordx4 v[234:237], v[234:235], off offset:32
	global_load_dwordx4 v[238:241], v[238:239], off offset:32
	global_load_dwordx4 v[242:245], v[242:243], off offset:32
	v_lshl_add_u64 v[132:133], v[116:117], 0, s[76:77]
	v_add_u32_e32 v156, v154, v139
	ds_read_b128 v[76:79], v156
	ds_read_b128 v[124:127], v156 offset:16
	ds_read_b128 v[72:75], v154 offset:16896
	ds_read_b128 v[68:71], v154 offset:16912
	s_waitcnt lgkmcnt(1)
	v_sub_f32_e32 v128, v76, v72
	v_sub_f32_e32 v129, v77, v73
	v_sub_f32_e32 v130, v78, v74
	v_sub_f32_e32 v131, v79, v75
	v_mul_f32_e32 v128, 0x3fb8aa3b, v128
	v_mul_f32_e32 v129, 0x3fb8aa3b, v129
	v_mul_f32_e32 v130, 0x3fb8aa3b, v130
	v_mul_f32_e32 v131, 0x3fb8aa3b, v131
	v_exp_f32_e32 v128, v128
	v_exp_f32_e32 v129, v129
	v_exp_f32_e32 v130, v130
	v_exp_f32_e32 v131, v131
	s_waitcnt lgkmcnt(0)
	v_sub_f32_e32 v155, v124, v68
	v_mul_f32_e32 v76, 0x3fb8aa3b, v76
	v_mul_f32_e32 v155, 0x3fb8aa3b, v155
	v_exp_f32_e32 v162, v76
	v_mul_f32_e32 v76, 0x3fb8aa3b, v77
	v_exp_f32_e32 v158, v155
	v_sub_f32_e32 v155, v125, v69
	v_exp_f32_e32 v163, v76
	v_mul_f32_e32 v155, 0x3fb8aa3b, v155
	v_exp_f32_e32 v159, v155
	v_sub_f32_e32 v155, v126, v70
	v_mul_f32_e32 v155, 0x3fb8aa3b, v155
	v_exp_f32_e32 v160, v155
	v_sub_f32_e32 v155, v127, v71
	v_mul_f32_e32 v155, 0x3fb8aa3b, v155
	v_exp_f32_e32 v161, v155
	v_add_u32_e32 v155, v154, v142
	s_waitcnt vmcnt(9)
	v_lshlrev_b32_e32 v164, 16, v206
	v_and_b32_e32 v165, 0xffff0000, v206
	v_mul_f32_e32 v64, 0x3fb8aa3b, v78
	v_exp_f32_e32 v78, v64
	v_mul_f32_e32 v64, 0x3fb8aa3b, v79
	v_exp_f32_e32 v79, v64
	v_lshlrev_b32_e32 v64, 16, v207
	v_and_b32_e32 v65, 0xffff0000, v207
	v_pk_mul_f32 v[76:77], v[128:129], v[164:165]
	v_pk_mul_f32 v[130:131], v[130:131], v[64:65]
	v_cvt_pk_bf16_f32 v76, v76, v77
	v_cvt_pk_bf16_f32 v77, v130, v131
	v_pk_mul_f32 v[130:131], v[78:79], v[64:65]
	v_mul_f32_e32 v64, 0x3fb8aa3b, v124
	v_mul_f32_e32 v65, 0x3fb8aa3b, v125
	v_exp_f32_e32 v64, v64
	v_exp_f32_e32 v65, v65
	v_lshlrev_b32_e32 v124, 16, v208
	v_and_b32_e32 v125, 0xffff0000, v208
	v_pk_mul_f32 v[78:79], v[158:159], v[124:125]
	v_pk_mul_f32 v[124:125], v[64:65], v[124:125]
	v_mul_f32_e32 v64, 0x3fb8aa3b, v126
	v_mul_f32_e32 v65, 0x3fb8aa3b, v127
	v_exp_f32_e32 v64, v64
	v_exp_f32_e32 v65, v65
	v_lshlrev_b32_e32 v66, 16, v209
	v_and_b32_e32 v67, 0xffff0000, v209
	v_pk_mul_f32 v[126:127], v[160:161], v[66:67]
	v_pk_mul_f32 v[128:129], v[162:163], v[164:165]
	v_cvt_pk_bf16_f32 v78, v78, v79
	v_cvt_pk_bf16_f32 v79, v126, v127
	v_pk_mul_f32 v[126:127], v[64:65], v[66:67]
	v_cvt_pk_bf16_f32 v66, v124, v125
	v_lshl_add_u64 v[124:125], v[122:123], 0, s[76:77]
	v_cvt_pk_bf16_f32 v64, v128, v129
	v_cvt_pk_bf16_f32 v67, v126, v127
	ds_read_b128 v[158:161], v155
	ds_read_b128 v[162:165], v155 offset:16
	v_cvt_pk_bf16_f32 v65, v130, v131
	s_waitcnt lgkmcnt(1)
	v_sub_f32_e32 v130, v72, v158
	v_sub_f32_e32 v131, v73, v159
	v_mul_f32_e32 v130, 0x3fb8aa3b, v130
	v_mul_f32_e32 v131, 0x3fb8aa3b, v131
	v_exp_f32_e32 v130, v130
	v_exp_f32_e32 v131, v131
	s_waitcnt vmcnt(8)
	v_lshlrev_b32_e32 v158, 16, v210
	v_and_b32_e32 v159, 0xffff0000, v210
	v_sub_f32_e32 v126, v74, v160
	v_mul_f32_e32 v126, 0x3fb8aa3b, v126
	v_pk_mul_f32 v[130:131], v[130:131], v[158:159]
	v_exp_f32_e32 v158, v126
	v_sub_f32_e32 v126, v75, v161
	v_mul_f32_e32 v126, 0x3fb8aa3b, v126
	v_exp_f32_e32 v159, v126
	v_lshlrev_b32_e32 v126, 16, v211
	v_and_b32_e32 v127, 0xffff0000, v211
	v_lshlrev_b32_e32 v160, 16, v212
	v_pk_mul_f32 v[158:159], v[158:159], v[126:127]
	s_waitcnt lgkmcnt(0)
	v_sub_f32_e32 v126, v68, v162
	v_sub_f32_e32 v127, v69, v163
	v_mul_f32_e32 v126, 0x3fb8aa3b, v126
	v_mul_f32_e32 v127, 0x3fb8aa3b, v127
	v_exp_f32_e32 v126, v126
	v_exp_f32_e32 v127, v127
	v_and_b32_e32 v161, 0xffff0000, v212
	v_lshlrev_b32_e32 v128, 16, v213
	v_and_b32_e32 v129, 0xffff0000, v213
	v_pk_mul_f32 v[160:161], v[126:127], v[160:161]
	v_sub_f32_e32 v126, v70, v164
	v_sub_f32_e32 v127, v71, v165
	v_mul_f32_e32 v126, 0x3fb8aa3b, v126
	v_mul_f32_e32 v127, 0x3fb8aa3b, v127
	v_exp_f32_e32 v126, v126
	v_exp_f32_e32 v127, v127
	s_nop 0
	v_pk_mul_f32 v[162:163], v[126:127], v[128:129]
	v_cvt_pk_bf16_f32 v126, v130, v131
	v_cvt_pk_bf16_f32 v127, v158, v159
	v_cvt_pk_bf16_f32 v128, v160, v161
	v_cvt_pk_bf16_f32 v129, v162, v163
	s_nop 1
	v_mfma_f32_32x32x16_bf16 v[48:63], v[126:129], v[76:79], v[48:63]
	v_lshl_add_u64 v[126:127], v[120:121], 0, s[76:77]
	ds_read_b128 v[158:161], v155 offset:16896
	ds_read_b128 v[162:165], v155 offset:16912
	s_waitcnt lgkmcnt(1)
	v_sub_f32_e32 v74, v74, v160
	v_sub_f32_e32 v75, v75, v161
	v_mul_f32_e32 v74, 0x3fb8aa3b, v74
	v_mul_f32_e32 v75, 0x3fb8aa3b, v75
	s_waitcnt lgkmcnt(0)
	v_sub_f32_e32 v68, v68, v162
	v_sub_f32_e32 v69, v69, v163
	v_exp_f32_e32 v74, v74
	v_exp_f32_e32 v75, v75
	v_mul_f32_e32 v68, 0x3fb8aa3b, v68
	v_mul_f32_e32 v69, 0x3fb8aa3b, v69
	v_exp_f32_e32 v68, v68
	v_exp_f32_e32 v69, v69
	v_sub_f32_e32 v72, v72, v158
	v_sub_f32_e32 v73, v73, v159
	v_mul_f32_e32 v72, 0x3fb8aa3b, v72
	v_mul_f32_e32 v73, 0x3fb8aa3b, v73
	v_exp_f32_e32 v72, v72
	v_exp_f32_e32 v73, v73
	s_waitcnt vmcnt(7)
; #define MFMA32(a, b, c) __builtin_amdgcn_mfma_f32_32x32x16_bf16((a), (b), (c), 0, 0, 0)
; DI float bflo(unsigned p) { return __uint_as_float(p << 16); }
; DI float bfhi(unsigned p) { return __uint_as_float(p & 0xffff0000u); }
; DI void hgrn_out(const Params& P, int l, int item, char* smem) {
;     ...
;     _Pragma("unroll 2") for (int ks = 0; ks < 8; ++ks) {
;       const int dk0 = 16 * ks + 8 * h;
;       u32x4 qraw = *(const u32x4*)(P.hq + (size_t)(t0 + t) * 1024 + head * 128 + dk0);
;       float4 bt0 = *(const float4*)(bs + t * BST + dk0), bt1 = *(const float4*)(bs + t * BST + dk0 + 4);
;       float4 rf0 = *(const float4*)(bs + 32 * BST + dk0), rf1 = *(const float4*)(bs + 32 * BST + dk0 + 4);
;       float q0 = bflo(qraw[0]), q1 = bfhi(qraw[0]), q2 = bflo(qraw[1]), q3 = bfhi(qraw[1]);
;       float q4 = bflo(qraw[2]), q5 = bfhi(qraw[2]), q6 = bflo(qraw[3]), q7 = bfhi(qraw[3]);
;       bf16x8 qref = pack8(q0 * __expf(bt0.x - rf0.x), q1 * __expf(bt0.y - rf0.y), q2 * __expf(bt0.z - rf0.z), q3 * __expf(bt0.w - rf0.w),
;                           q4 * __expf(bt1.x - rf1.x), q5 * __expf(bt1.y - rf1.y), q6 * __expf(bt1.z - rf1.z), q7 * __expf(bt1.w - rf1.w));
;       bf16x8 qint = pack8(q0 * __expf(bt0.x), q1 * __expf(bt0.y), q2 * __expf(bt0.z), q3 * __expf(bt0.w),
;                           q4 * __expf(bt1.x), q5 * __expf(bt1.y), q6 * __expf(bt1.z), q7 * __expf(bt1.w));
;       _Pragma("unroll") for (int st = 0; st < 2; ++st) {
;         const int s_ = 32 * st + r;
;         u32x4 kraw = *(const u32x4*)(kk + (size_t)(t0 + s_) * 1024 + head * 128 + dk0);
;         float4 b0 = *(const float4*)(bs + s_ * BST + dk0), b1 = *(const float4*)(bs + s_ * BST + dk0 + 4);
;         bf16x8 kt = pack8(bflo(kraw[0]) * __expf(rf0.x - b0.x), bfhi(kraw[0]) * __expf(rf0.y - b0.y),
;                           bflo(kraw[1]) * __expf(rf0.z - b0.z), bfhi(kraw[1]) * __expf(rf0.w - b0.w),
;                           bflo(kraw[2]) * __expf(rf1.x - b1.x), bfhi(kraw[2]) * __expf(rf1.y - b1.y),
;                           bflo(kraw[3]) * __expf(rf1.z - b1.z), bfhi(kraw[3]) * __expf(rf1.w - b1.w));
;         sc[st] = MFMA32(kt, qref, sc[st]);
;       }
;       _Pragma("unroll") for (int mi = 0; mi < 2; ++mi) {
;         const int dv = 32 * (2 * dh + mi) + r;
;         bf16x8 sfr = *(const bf16x8*)(stp + dv * 128 + dk0);
;         o[mi] = MFMA32(sfr, qint, o[mi]);
;       }
;     }
	v_lshlrev_b32_e32 v158, 16, v214
	v_and_b32_e32 v159, 0xffff0000, v214
	v_lshlrev_b32_e32 v128, 16, v215
	v_and_b32_e32 v129, 0xffff0000, v215
	v_pk_mul_f32 v[74:75], v[74:75], v[128:129]
	v_lshlrev_b32_e32 v128, 16, v216
	v_and_b32_e32 v129, 0xffff0000, v216
	v_pk_mul_f32 v[128:129], v[68:69], v[128:129]
	v_sub_f32_e32 v68, v70, v164
	v_sub_f32_e32 v69, v71, v165
	v_mul_f32_e32 v68, 0x3fb8aa3b, v68
	v_mul_f32_e32 v69, 0x3fb8aa3b, v69
	v_exp_f32_e32 v68, v68
	v_exp_f32_e32 v69, v69
	v_lshlrev_b32_e32 v70, 16, v217
	v_and_b32_e32 v71, 0xffff0000, v217
	v_pk_mul_f32 v[72:73], v[72:73], v[158:159]
	v_pk_mul_f32 v[130:131], v[68:69], v[70:71]
	v_cvt_pk_bf16_f32 v68, v72, v73
	v_cvt_pk_bf16_f32 v69, v74, v75
	v_cvt_pk_bf16_f32 v70, v128, v129
	v_cvt_pk_bf16_f32 v71, v130, v131
	v_lshl_add_u64 v[130:131], v[118:119], 0, s[76:77]
	v_add_co_u32_e32 v128, vcc, s33, v130
	v_mfma_f32_32x32x16_bf16 v[32:47], v[68:71], v[76:79], v[32:47]
	v_addc_co_u32_e32 v129, vcc, 0, v131, vcc
	s_add_u32 s76, s76, 64
	s_addc_u32 s77, s77, 0
	s_cmpk_eq_i32 s76, 0x100
	s_waitcnt vmcnt(6)
	v_mfma_f32_32x32x16_bf16 v[16:31], v[218:221], v[64:67], v[16:31]
	s_waitcnt vmcnt(5)
	v_mfma_f32_32x32x16_bf16 v[0:15], v[222:225], v[64:67], v[0:15]
	ds_read_b128 v[76:79], v156 offset:64
	ds_read_b128 v[156:159], v156 offset:80
	ds_read_b128 v[72:75], v154 offset:16960
	ds_read_b128 v[68:71], v154 offset:16976
	v_add_u32_e32 v154, 0x80, v154
	s_waitcnt lgkmcnt(1)
	v_sub_f32_e32 v132, v76, v72
	v_sub_f32_e32 v133, v77, v73
	v_sub_f32_e32 v160, v78, v74
	v_sub_f32_e32 v161, v79, v75
	v_mul_f32_e32 v132, 0x3fb8aa3b, v132
	v_mul_f32_e32 v133, 0x3fb8aa3b, v133
	v_mul_f32_e32 v160, 0x3fb8aa3b, v160
	v_mul_f32_e32 v161, 0x3fb8aa3b, v161
	v_exp_f32_e32 v132, v132
	v_exp_f32_e32 v133, v133
	v_exp_f32_e32 v160, v160
	v_exp_f32_e32 v161, v161
	v_mul_f32_e32 v76, 0x3fb8aa3b, v76
	v_exp_f32_e32 v166, v76
	v_mul_f32_e32 v76, 0x3fb8aa3b, v77
	s_waitcnt lgkmcnt(0)
	v_sub_f32_e32 v162, v156, v68
	v_sub_f32_e32 v163, v157, v69
	v_exp_f32_e32 v167, v76
	v_mul_f32_e32 v162, 0x3fb8aa3b, v162
	v_mul_f32_e32 v163, 0x3fb8aa3b, v163
	v_exp_f32_e32 v162, v162
	v_exp_f32_e32 v163, v163
	v_sub_f32_e32 v164, v158, v70
	v_sub_f32_e32 v165, v159, v71
	v_mul_f32_e32 v164, 0x3fb8aa3b, v164
	v_mul_f32_e32 v165, 0x3fb8aa3b, v165
	v_exp_f32_e32 v164, v164
	v_exp_f32_e32 v165, v165
	s_waitcnt vmcnt(4)
	v_lshlrev_b32_e32 v168, 16, v226
	v_and_b32_e32 v169, 0xffff0000, v226
	v_mul_f32_e32 v64, 0x3fb8aa3b, v78
	v_exp_f32_e32 v78, v64
	v_mul_f32_e32 v64, 0x3fb8aa3b, v79
	v_exp_f32_e32 v79, v64
	v_lshlrev_b32_e32 v64, 16, v227
	v_and_b32_e32 v65, 0xffff0000, v227
	v_pk_mul_f32 v[76:77], v[132:133], v[168:169]
	v_pk_mul_f32 v[160:161], v[160:161], v[64:65]
	v_cvt_pk_bf16_f32 v76, v76, v77
	v_cvt_pk_bf16_f32 v77, v160, v161
	v_pk_mul_f32 v[160:161], v[78:79], v[64:65]
	v_mul_f32_e32 v64, 0x3fb8aa3b, v156
	v_mul_f32_e32 v65, 0x3fb8aa3b, v157
	v_exp_f32_e32 v64, v64
	v_exp_f32_e32 v65, v65
	v_lshlrev_b32_e32 v156, 16, v228
	v_and_b32_e32 v157, 0xffff0000, v228
	v_pk_mul_f32 v[78:79], v[162:163], v[156:157]
	v_pk_mul_f32 v[156:157], v[64:65], v[156:157]
	v_mul_f32_e32 v64, 0x3fb8aa3b, v158
	v_mul_f32_e32 v65, 0x3fb8aa3b, v159
	v_exp_f32_e32 v64, v64
	v_exp_f32_e32 v65, v65
	v_lshlrev_b32_e32 v66, 16, v229
	v_and_b32_e32 v67, 0xffff0000, v229
	v_pk_mul_f32 v[158:159], v[164:165], v[66:67]
	v_cvt_pk_bf16_f32 v78, v78, v79
	v_cvt_pk_bf16_f32 v79, v158, v159
	v_pk_mul_f32 v[158:159], v[64:65], v[66:67]
	v_cvt_pk_bf16_f32 v66, v156, v157
	v_cvt_pk_bf16_f32 v67, v158, v159
	v_pk_mul_f32 v[132:133], v[166:167], v[168:169]
	v_cvt_pk_bf16_f32 v65, v160, v161
	ds_read_b128 v[160:163], v155 offset:64
	ds_read_b128 v[164:167], v155 offset:80
	v_cvt_pk_bf16_f32 v64, v132, v133
	s_waitcnt lgkmcnt(1)
	v_sub_f32_e32 v124, v72, v160
	v_sub_f32_e32 v125, v73, v161
	v_mul_f32_e32 v124, 0x3fb8aa3b, v124
	v_mul_f32_e32 v125, 0x3fb8aa3b, v125
	v_exp_f32_e32 v124, v124
	v_exp_f32_e32 v125, v125
	s_waitcnt vmcnt(3)
	v_lshlrev_b32_e32 v132, 16, v230
	v_and_b32_e32 v133, 0xffff0000, v230
	v_pk_mul_f32 v[124:125], v[124:125], v[132:133]
	v_sub_f32_e32 v132, v74, v162
	v_sub_f32_e32 v133, v75, v163
	v_mul_f32_e32 v132, 0x3fb8aa3b, v132
	v_mul_f32_e32 v133, 0x3fb8aa3b, v133
	v_exp_f32_e32 v132, v132
	v_exp_f32_e32 v133, v133
	v_lshlrev_b32_e32 v156, 16, v231
	v_and_b32_e32 v157, 0xffff0000, v231
	v_lshlrev_b32_e32 v160, 16, v232
	v_pk_mul_f32 v[132:133], v[132:133], v[156:157]
	s_waitcnt lgkmcnt(0)
	v_sub_f32_e32 v156, v68, v164
	v_sub_f32_e32 v157, v69, v165
	v_mul_f32_e32 v156, 0x3fb8aa3b, v156
	v_mul_f32_e32 v157, 0x3fb8aa3b, v157
	v_exp_f32_e32 v156, v156
	v_exp_f32_e32 v157, v157
	v_and_b32_e32 v161, 0xffff0000, v232
	v_lshlrev_b32_e32 v158, 16, v233
	v_and_b32_e32 v159, 0xffff0000, v233
	v_pk_mul_f32 v[160:161], v[156:157], v[160:161]
	v_sub_f32_e32 v156, v70, v166
	v_sub_f32_e32 v157, v71, v167
	v_mul_f32_e32 v156, 0x3fb8aa3b, v156
	v_mul_f32_e32 v157, 0x3fb8aa3b, v157
	v_exp_f32_e32 v156, v156
	v_exp_f32_e32 v157, v157
	s_nop 0
	v_pk_mul_f32 v[162:163], v[156:157], v[158:159]
	v_cvt_pk_bf16_f32 v156, v124, v125
	v_cvt_pk_bf16_f32 v157, v132, v133
	v_cvt_pk_bf16_f32 v158, v160, v161
	v_cvt_pk_bf16_f32 v159, v162, v163
	s_waitcnt vmcnt(2)
	v_lshlrev_b32_e32 v132, 16, v234
	v_mfma_f32_32x32x16_bf16 v[48:63], v[156:159], v[76:79], v[48:63]
	ds_read_b128 v[156:159], v155 offset:16960
	ds_read_b128 v[160:163], v155 offset:16976
	v_and_b32_e32 v133, 0xffff0000, v234
	v_lshlrev_b32_e32 v124, 16, v235
	v_and_b32_e32 v125, 0xffff0000, v235
	s_waitcnt lgkmcnt(1)
	v_sub_f32_e32 v74, v74, v158
	v_sub_f32_e32 v75, v75, v159
	v_mul_f32_e32 v74, 0x3fb8aa3b, v74
	v_mul_f32_e32 v75, 0x3fb8aa3b, v75
	s_waitcnt lgkmcnt(0)
	v_sub_f32_e32 v68, v68, v160
	v_sub_f32_e32 v69, v69, v161
	v_exp_f32_e32 v74, v74
	v_exp_f32_e32 v75, v75
	v_mul_f32_e32 v68, 0x3fb8aa3b, v68
	v_mul_f32_e32 v69, 0x3fb8aa3b, v69
	v_exp_f32_e32 v68, v68
	v_exp_f32_e32 v69, v69
	v_pk_mul_f32 v[74:75], v[74:75], v[124:125]
	v_lshlrev_b32_e32 v124, 16, v236
	v_and_b32_e32 v125, 0xffff0000, v236
	v_sub_f32_e32 v72, v72, v156
	v_sub_f32_e32 v73, v73, v157
	v_pk_mul_f32 v[124:125], v[68:69], v[124:125]
	v_sub_f32_e32 v68, v70, v162
	v_sub_f32_e32 v69, v71, v163
	v_mul_f32_e32 v72, 0x3fb8aa3b, v72
	v_mul_f32_e32 v73, 0x3fb8aa3b, v73
	v_mul_f32_e32 v68, 0x3fb8aa3b, v68
	v_mul_f32_e32 v69, 0x3fb8aa3b, v69
	v_exp_f32_e32 v72, v72
	v_exp_f32_e32 v73, v73
	v_exp_f32_e32 v68, v68
	v_exp_f32_e32 v69, v69
	v_lshlrev_b32_e32 v70, 16, v237
	v_and_b32_e32 v71, 0xffff0000, v237
	v_pk_mul_f32 v[72:73], v[72:73], v[132:133]
	v_pk_mul_f32 v[126:127], v[68:69], v[70:71]
	v_cvt_pk_bf16_f32 v68, v72, v73
	v_cvt_pk_bf16_f32 v69, v74, v75
	v_cvt_pk_bf16_f32 v70, v124, v125
	v_cvt_pk_bf16_f32 v71, v126, v127
	s_nop 1
	v_mfma_f32_32x32x16_bf16 v[32:47], v[68:71], v[76:79], v[32:47]
	s_waitcnt vmcnt(1)
	v_mfma_f32_32x32x16_bf16 v[16:31], v[238:241], v[64:67], v[16:31]
	s_waitcnt vmcnt(0)
	v_mfma_f32_32x32x16_bf16 v[0:15], v[242:245], v[64:67], v[0:15]
	s_cbranch_scc0 .LBB0_743
; DI int crow(int i, int h) { return (i & 3) + 8 * (i >> 2) + 4 * h; }
; DI void hgrn_out(const Params& P, int l, int item, char* smem) {
;     ...
;     _Pragma("unroll") for (int st = 0; st < 2; ++st) {
;       _Pragma("unroll") for (int i = 0; i < 16; ++i) {
;         const int s_ = 32 * st + crow(i, h);
;         const bool ok = dir ? (s_ >= t) : (s_ <= t);
;         sc[st][i] = ok ? sc[st][i] : 0.f;
;       }
;     }
	v_readlane_b32 s4, v247, 16
	v_readlane_b32 s5, v247, 17
	s_mov_b32 s76, 1
	s_nop 0
	v_cndmask_b32_e64 v64, 0, 1, s[4:5]
	v_readlane_b32 s4, v249, 34
	v_readlane_b32 s5, v249, 35
	s_nop 1
	v_cndmask_b32_e64 v65, 0, 1, s[4:5]
	v_cndmask_b32_e64 v64, v65, v64, s[74:75]
	v_readlane_b32 s4, v247, 20
	v_and_b32_e32 v64, 1, v64
	v_readlane_b32 s5, v247, 21
	v_cmp_eq_u32_e32 vcc, 1, v64
	s_nop 0
	v_cndmask_b32_e64 v64, 0, 1, s[4:5]
	v_readlane_b32 s4, v247, 18
	v_readlane_b32 s5, v247, 19
	v_cndmask_b32_e32 v48, 0, v48, vcc
	s_nop 0
	v_cndmask_b32_e64 v65, 0, 1, s[4:5]
	v_cndmask_b32_e64 v64, v65, v64, s[74:75]
	v_readlane_b32 s4, v247, 24
	v_and_b32_e32 v64, 1, v64
	v_readlane_b32 s5, v247, 25
	v_cmp_eq_u32_e32 vcc, 1, v64
	s_nop 0
	v_cndmask_b32_e64 v64, 0, 1, s[4:5]
	v_readlane_b32 s4, v247, 22
	v_readlane_b32 s5, v247, 23
	v_cndmask_b32_e32 v49, 0, v49, vcc
	s_nop 0
	v_cndmask_b32_e64 v65, 0, 1, s[4:5]
	v_cndmask_b32_e64 v64, v65, v64, s[74:75]
	v_readlane_b32 s4, v247, 28
	v_and_b32_e32 v64, 1, v64
	v_readlane_b32 s5, v247, 29
	v_cmp_eq_u32_e32 vcc, 1, v64
	s_nop 0
	v_cndmask_b32_e64 v64, 0, 1, s[4:5]
	v_readlane_b32 s4, v247, 26
	v_readlane_b32 s5, v247, 27
	v_cndmask_b32_e32 v50, 0, v50, vcc
	s_nop 0
	v_cndmask_b32_e64 v65, 0, 1, s[4:5]
	v_cndmask_b32_e64 v64, v65, v64, s[74:75]
	v_readlane_b32 s4, v247, 32
	v_and_b32_e32 v64, 1, v64
	v_readlane_b32 s5, v247, 33
	v_cmp_eq_u32_e32 vcc, 1, v64
	s_nop 0
	v_cndmask_b32_e64 v64, 0, 1, s[4:5]
	v_readlane_b32 s4, v247, 30
	v_readlane_b32 s5, v247, 31
	v_cndmask_b32_e32 v51, 0, v51, vcc
	s_nop 0
	v_cndmask_b32_e64 v65, 0, 1, s[4:5]
	v_cndmask_b32_e64 v64, v65, v64, s[74:75]
	v_readlane_b32 s4, v247, 36
	v_and_b32_e32 v64, 1, v64
	v_readlane_b32 s5, v247, 37
	v_cmp_eq_u32_e32 vcc, 1, v64
	s_nop 0
	v_cndmask_b32_e64 v64, 0, 1, s[4:5]
	v_readlane_b32 s4, v247, 34
	v_readlane_b32 s5, v247, 35
	v_cndmask_b32_e32 v52, 0, v52, vcc
	s_nop 0
	v_cndmask_b32_e64 v65, 0, 1, s[4:5]
	v_cndmask_b32_e64 v64, v65, v64, s[74:75]
	v_readlane_b32 s4, v247, 40
	v_and_b32_e32 v64, 1, v64
	v_readlane_b32 s5, v247, 41
	v_cmp_eq_u32_e32 vcc, 1, v64
	s_nop 0
	v_cndmask_b32_e64 v64, 0, 1, s[4:5]
	v_readlane_b32 s4, v247, 38
	v_readlane_b32 s5, v247, 39
	v_cndmask_b32_e32 v53, 0, v53, vcc
	s_nop 0
	v_cndmask_b32_e64 v65, 0, 1, s[4:5]
	v_cndmask_b32_e64 v64, v65, v64, s[74:75]
	v_readlane_b32 s4, v247, 44
	v_and_b32_e32 v64, 1, v64
	v_readlane_b32 s5, v247, 45
	v_cmp_eq_u32_e32 vcc, 1, v64
	s_nop 0
	v_cndmask_b32_e64 v64, 0, 1, s[4:5]
	v_readlane_b32 s4, v247, 42
	v_readlane_b32 s5, v247, 43
	v_cndmask_b32_e32 v54, 0, v54, vcc
	s_nop 0
	v_cndmask_b32_e64 v65, 0, 1, s[4:5]
	v_cndmask_b32_e64 v64, v65, v64, s[74:75]
	v_readlane_b32 s4, v247, 48
	v_and_b32_e32 v64, 1, v64
	v_readlane_b32 s5, v247, 49
	v_cmp_eq_u32_e32 vcc, 1, v64
	s_nop 0
	v_cndmask_b32_e64 v64, 0, 1, s[4:5]
	v_readlane_b32 s4, v247, 46
	v_readlane_b32 s5, v247, 47
	v_cndmask_b32_e32 v55, 0, v55, vcc
	s_nop 0
	v_cndmask_b32_e64 v65, 0, 1, s[4:5]
	v_cndmask_b32_e64 v64, v65, v64, s[74:75]
	v_readlane_b32 s4, v247, 52
	v_and_b32_e32 v64, 1, v64
	v_readlane_b32 s5, v247, 53
	v_cmp_eq_u32_e32 vcc, 1, v64
	s_nop 0
	v_cndmask_b32_e64 v64, 0, 1, s[4:5]
	v_readlane_b32 s4, v247, 50
	v_readlane_b32 s5, v247, 51
	v_cndmask_b32_e32 v56, 0, v56, vcc
	s_nop 0
	v_cndmask_b32_e64 v65, 0, 1, s[4:5]
	v_cndmask_b32_e64 v64, v65, v64, s[74:75]
	v_readlane_b32 s4, v247, 56
	v_and_b32_e32 v64, 1, v64
	v_readlane_b32 s5, v247, 57
	v_cmp_eq_u32_e32 vcc, 1, v64
	s_nop 0
	v_cndmask_b32_e64 v64, 0, 1, s[4:5]
	v_readlane_b32 s4, v247, 54
	v_readlane_b32 s5, v247, 55
	v_cndmask_b32_e32 v57, 0, v57, vcc
	s_nop 0
	v_cndmask_b32_e64 v65, 0, 1, s[4:5]
	v_cndmask_b32_e64 v64, v65, v64, s[74:75]
	v_readlane_b32 s4, v247, 60
	v_and_b32_e32 v64, 1, v64
	v_readlane_b32 s5, v247, 61
	v_cmp_eq_u32_e32 vcc, 1, v64
	s_nop 0
	v_cndmask_b32_e64 v64, 0, 1, s[4:5]
	v_readlane_b32 s4, v247, 58
	v_readlane_b32 s5, v247, 59
	v_cndmask_b32_e32 v58, 0, v58, vcc
	s_nop 0
	v_cndmask_b32_e64 v65, 0, 1, s[4:5]
	v_cndmask_b32_e64 v64, v65, v64, s[74:75]
	v_readlane_b32 s4, v246, 2
	v_and_b32_e32 v64, 1, v64
	v_readlane_b32 s5, v246, 3
	v_cmp_eq_u32_e32 vcc, 1, v64
	s_nop 0
	v_cndmask_b32_e64 v64, 0, 1, s[4:5]
	v_readlane_b32 s4, v247, 62
	v_readlane_b32 s5, v247, 63
	v_cndmask_b32_e32 v59, 0, v59, vcc
	s_nop 0
	v_cndmask_b32_e64 v65, 0, 1, s[4:5]
	v_cndmask_b32_e64 v64, v65, v64, s[74:75]
	v_readlane_b32 s4, v246, 6
	v_and_b32_e32 v64, 1, v64
	v_readlane_b32 s5, v246, 7
	v_cmp_eq_u32_e32 vcc, 1, v64
	s_nop 0
	v_cndmask_b32_e64 v64, 0, 1, s[4:5]
	v_readlane_b32 s4, v246, 4
	v_readlane_b32 s5, v246, 5
	v_cndmask_b32_e32 v60, 0, v60, vcc
	s_nop 0
	v_cndmask_b32_e64 v65, 0, 1, s[4:5]
	v_cndmask_b32_e64 v64, v65, v64, s[74:75]
	v_readlane_b32 s4, v246, 10
	v_and_b32_e32 v64, 1, v64
	v_readlane_b32 s5, v246, 11
	v_cmp_eq_u32_e32 vcc, 1, v64
	s_nop 0
	v_cndmask_b32_e64 v64, 0, 1, s[4:5]
	v_readlane_b32 s4, v246, 8
	v_readlane_b32 s5, v246, 9
	v_cndmask_b32_e32 v61, 0, v61, vcc
	s_nop 0
	v_cndmask_b32_e64 v65, 0, 1, s[4:5]
	v_cndmask_b32_e64 v64, v65, v64, s[74:75]
	v_readlane_b32 s4, v246, 12
	v_and_b32_e32 v64, 1, v64
	v_readlane_b32 s5, v246, 13
	v_cmp_eq_u32_e32 vcc, 1, v64
	v_cndmask_b32_e64 v64, 0, 1, s[84:85]
	v_cndmask_b32_e64 v65, 0, 1, s[4:5]
	v_cndmask_b32_e64 v64, v65, v64, s[74:75]
	v_and_b32_e32 v64, 1, v64
	v_cndmask_b32_e32 v62, 0, v62, vcc
	v_cmp_eq_u32_e32 vcc, 1, v64
	v_cndmask_b32_e64 v64, 0, 1, s[88:89]
	v_cndmask_b32_e64 v65, 0, 1, s[86:87]
	v_cndmask_b32_e64 v64, v65, v64, s[74:75]
	v_and_b32_e32 v64, 1, v64
	v_cndmask_b32_e32 v63, 0, v63, vcc
	v_cmp_eq_u32_e32 vcc, 1, v64
	v_cndmask_b32_e64 v65, 0, 1, s[90:91]
; #define MFMA32(a, b, c) __builtin_amdgcn_mfma_f32_32x32x16_bf16((a), (b), (c), 0, 0, 0)
; DI int crow(int i, int h) { return (i & 3) + 8 * (i >> 2) + 4 * h; }
; DI void hgrn_out(const Params& P, int l, int item, char* smem) {
;     ...
;     _Pragma("unroll") for (int st = 0; st < 2; ++st) {
;       _Pragma("unroll") for (int i = 0; i < 16; ++i) {
;         const int s_ = 32 * st + crow(i, h);
;         const bool ok = dir ? (s_ >= t) : (s_ <= t);
;         sc[st][i] = ok ? sc[st][i] : 0.f;
;       }
;     }
;     _Pragma("unroll") for (int st = 0; st < 2; ++st) {
;       _Pragma("unroll") for (int s2 = 0; s2 < 2; ++s2) {
;         bf16x8 pb = pack8(sc[st][8 * s2], sc[st][8 * s2 + 1], sc[st][8 * s2 + 2], sc[st][8 * s2 + 3],
;                           sc[st][8 * s2 + 4], sc[st][8 * s2 + 5], sc[st][8 * s2 + 6], sc[st][8 * s2 + 7]);
;         _Pragma("unroll") for (int mi = 0; mi < 2; ++mi) {
;           const int dv = 32 * (2 * dh + mi) + r;
;           const bf16_t* vp = P.hvt + (size_t)(head * 128 + dv) * TH + t0 + 32 * st + 16 * s2 + 4 * h;
;           s16x4 lo = *(const s16x4*)vp;
;           s16x4 hi = *(const s16x4*)(vp + 8);
;           bf16x8 va = __builtin_shufflevector(lo, hi, 0, 1, 2, 3, 4, 5, 6, 7);
;           o[mi] = MFMA32(va, pb, o[mi]);
;         }
;       }
;     }
;   }
;   float sq = 0.f;
;   _Pragma("unroll") for (int mi = 0; mi < 2; ++mi) {
;     _Pragma("unroll") for (int i = 0; i < 16; ++i) sq += o[mi][i] * o[mi][i];
;   }
;   sq += __shfl_xor(sq, 32);
;   if (h == 0) ssq[dh * 64 + t] = sq;
	s_nop 0
	v_cndmask_b32_e32 v64, 0, v32, vcc
	v_cndmask_b32_e64 v32, 0, 1, s[92:93]
	v_cndmask_b32_e64 v32, v65, v32, s[74:75]
	v_and_b32_e32 v32, 1, v32
	v_cmp_eq_u32_e32 vcc, 1, v32
	v_cndmask_b32_e64 v32, 0, 1, s[96:97]
	s_nop 0
	v_cndmask_b32_e32 v65, 0, v33, vcc
	v_cndmask_b32_e64 v33, 0, 1, s[94:95]
	v_cndmask_b32_e64 v32, v33, v32, s[74:75]
	v_and_b32_e32 v32, 1, v32
	v_cmp_eq_u32_e32 vcc, 1, v32
	v_cndmask_b32_e64 v32, 0, 1, s[20:21]
	v_cndmask_b32_e64 v33, 0, 1, s[2:3]
	v_cndmask_b32_e64 v32, v33, v32, s[74:75]
	v_and_b32_e32 v32, 1, v32
	v_cndmask_b32_e32 v66, 0, v34, vcc
	v_cmp_eq_u32_e32 vcc, 1, v32
	v_cndmask_b32_e64 v32, 0, 1, s[24:25]
	v_cndmask_b32_e64 v33, 0, 1, s[22:23]
	v_cndmask_b32_e64 v32, v33, v32, s[74:75]
	v_and_b32_e32 v32, 1, v32
	v_cndmask_b32_e32 v67, 0, v35, vcc
	v_cmp_eq_u32_e32 vcc, 1, v32
	v_cndmask_b32_e64 v32, 0, 1, s[28:29]
	v_cndmask_b32_e64 v33, 0, 1, s[26:27]
	v_cndmask_b32_e64 v32, v33, v32, s[74:75]
	v_and_b32_e32 v32, 1, v32
	v_cndmask_b32_e32 v68, 0, v36, vcc
	v_cmp_eq_u32_e32 vcc, 1, v32
	v_cndmask_b32_e64 v32, 0, 1, s[34:35]
	v_cndmask_b32_e64 v33, 0, 1, s[30:31]
	v_cndmask_b32_e64 v32, v33, v32, s[74:75]
	v_and_b32_e32 v32, 1, v32
	v_cndmask_b32_e32 v69, 0, v37, vcc
	v_cmp_eq_u32_e32 vcc, 1, v32
	v_cndmask_b32_e64 v32, 0, 1, s[0:1]
	v_cndmask_b32_e64 v33, 0, 1, s[36:37]
	v_cndmask_b32_e64 v32, v33, v32, s[74:75]
	v_and_b32_e32 v32, 1, v32
	v_cndmask_b32_e32 v70, 0, v38, vcc
	v_cmp_eq_u32_e32 vcc, 1, v32
	v_cndmask_b32_e64 v32, 0, 1, s[40:41]
	v_cndmask_b32_e64 v33, 0, 1, s[38:39]
	v_cndmask_b32_e64 v32, v33, v32, s[74:75]
	v_and_b32_e32 v32, 1, v32
	v_cndmask_b32_e32 v71, 0, v39, vcc
	v_cmp_eq_u32_e32 vcc, 1, v32
	v_cndmask_b32_e64 v32, 0, 1, s[44:45]
	v_cndmask_b32_e64 v33, 0, 1, s[42:43]
	v_cndmask_b32_e64 v32, v33, v32, s[74:75]
	v_and_b32_e32 v32, 1, v32
	v_cndmask_b32_e32 v72, 0, v40, vcc
	v_cmp_eq_u32_e32 vcc, 1, v32
	v_cndmask_b32_e64 v32, 0, 1, s[48:49]
	v_cndmask_b32_e64 v33, 0, 1, s[46:47]
	v_cndmask_b32_e64 v32, v33, v32, s[74:75]
	v_and_b32_e32 v32, 1, v32
	v_cndmask_b32_e32 v73, 0, v41, vcc
	v_cmp_eq_u32_e32 vcc, 1, v32
	v_cndmask_b32_e64 v32, 0, 1, s[52:53]
	v_cndmask_b32_e64 v33, 0, 1, s[50:51]
	v_cndmask_b32_e64 v32, v33, v32, s[74:75]
	v_and_b32_e32 v32, 1, v32
	v_cndmask_b32_e32 v74, 0, v42, vcc
	v_cmp_eq_u32_e32 vcc, 1, v32
	v_cndmask_b32_e64 v32, 0, 1, s[56:57]
	v_cndmask_b32_e64 v33, 0, 1, s[54:55]
	v_cndmask_b32_e64 v32, v33, v32, s[74:75]
	v_and_b32_e32 v32, 1, v32
	v_cndmask_b32_e32 v75, 0, v43, vcc
	v_cmp_eq_u32_e32 vcc, 1, v32
	v_cndmask_b32_e64 v32, 0, 1, s[60:61]
	v_cndmask_b32_e64 v33, 0, 1, s[58:59]
	v_cndmask_b32_e64 v32, v33, v32, s[74:75]
	v_and_b32_e32 v32, 1, v32
	v_cndmask_b32_e32 v44, 0, v44, vcc
	v_cmp_eq_u32_e32 vcc, 1, v32
	v_cndmask_b32_e64 v32, 0, 1, s[64:65]
	v_cndmask_b32_e64 v33, 0, 1, s[62:63]
	v_cndmask_b32_e64 v32, v33, v32, s[74:75]
	v_and_b32_e32 v32, 1, v32
	v_cndmask_b32_e32 v45, 0, v45, vcc
	v_cmp_eq_u32_e32 vcc, 1, v32
	v_cndmask_b32_e64 v32, 0, 1, s[68:69]
	v_cndmask_b32_e64 v33, 0, 1, s[66:67]
	v_cndmask_b32_e64 v32, v33, v32, s[74:75]
	v_and_b32_e32 v32, 1, v32
	v_cndmask_b32_e32 v46, 0, v46, vcc
	v_cmp_eq_u32_e32 vcc, 1, v32
	global_load_dwordx2 v[32:33], v[86:87], off
	global_load_dwordx2 v[34:35], v[86:87], off offset:16
	global_load_dwordx2 v[36:37], v[88:89], off
	v_cvt_pk_bf16_f32 v40, v48, v49
	v_cvt_pk_bf16_f32 v41, v50, v51
	v_cvt_pk_bf16_f32 v42, v52, v53
	v_cvt_pk_bf16_f32 v43, v54, v55
	v_cndmask_b32_e32 v47, 0, v47, vcc
	s_and_b64 vcc, exec, s[70:71]
	s_waitcnt vmcnt(1)
	v_mfma_f32_32x32x16_bf16 v[16:31], v[32:35], v[40:43], v[16:31]
	global_load_dwordx2 v[38:39], v[88:89], off offset:16
	global_load_dwordx2 v[32:33], v[86:87], off offset:32
	s_mov_b64 s[74:75], 0
	s_waitcnt vmcnt(1)
	v_mfma_f32_32x32x16_bf16 v[0:15], v[36:39], v[40:43], v[0:15]
	global_load_dwordx2 v[34:35], v[86:87], off offset:48
	global_load_dwordx2 v[36:37], v[90:91], off
	v_cvt_pk_bf16_f32 v40, v56, v57
	v_cvt_pk_bf16_f32 v41, v58, v59
	v_cvt_pk_bf16_f32 v42, v60, v61
	v_cvt_pk_bf16_f32 v43, v62, v63
	s_waitcnt vmcnt(1)
	s_nop 0
	v_mfma_f32_32x32x16_bf16 v[16:31], v[32:35], v[40:43], v[16:31]
	global_load_dwordx2 v[38:39], v[90:91], off offset:16
	global_load_dwordx2 v[32:33], v[86:87], off offset:64
	s_waitcnt vmcnt(1)
	v_mfma_f32_32x32x16_bf16 v[0:15], v[36:39], v[40:43], v[0:15]
	global_load_dwordx2 v[34:35], v[86:87], off offset:80
	global_load_dwordx2 v[36:37], v[92:93], off
	v_cvt_pk_bf16_f32 v40, v64, v65
	v_cvt_pk_bf16_f32 v41, v66, v67
	v_cvt_pk_bf16_f32 v42, v68, v69
	v_cvt_pk_bf16_f32 v43, v70, v71
	s_waitcnt vmcnt(1)
	s_nop 0
	v_mfma_f32_32x32x16_bf16 v[16:31], v[32:35], v[40:43], v[16:31]
	global_load_dwordx2 v[38:39], v[92:93], off offset:16
	global_load_dwordx2 v[32:33], v[86:87], off offset:96
	s_waitcnt vmcnt(1)
	v_mfma_f32_32x32x16_bf16 v[0:15], v[36:39], v[40:43], v[0:15]
	global_load_dwordx2 v[34:35], v[86:87], off offset:112
	global_load_dwordx2 v[36:37], v[94:95], off
	global_load_dwordx2 v[38:39], v[94:95], off offset:16
	v_cvt_pk_bf16_f32 v40, v72, v73
	v_cvt_pk_bf16_f32 v41, v74, v75
	v_cvt_pk_bf16_f32 v42, v44, v45
	v_cvt_pk_bf16_f32 v43, v46, v47
	s_waitcnt vmcnt(2)
	s_nop 0
	v_mfma_f32_32x32x16_bf16 v[16:31], v[32:35], v[40:43], v[16:31]
	s_waitcnt vmcnt(0)
	v_mfma_f32_32x32x16_bf16 v[0:15], v[36:39], v[40:43], v[0:15]
	s_cbranch_vccz .LBB0_735
	s_nop 8
	v_mul_f32_e32 v32, v17, v17
	v_fmac_f32_e32 v32, v16, v16
	v_fmac_f32_e32 v32, v18, v18
	v_fmac_f32_e32 v32, v19, v19
	v_fmac_f32_e32 v32, v20, v20
	v_fmac_f32_e32 v32, v21, v21
	v_fmac_f32_e32 v32, v22, v22
	v_fmac_f32_e32 v32, v23, v23
	v_fmac_f32_e32 v32, v24, v24
	v_fmac_f32_e32 v32, v25, v25
	v_fmac_f32_e32 v32, v26, v26
	v_fmac_f32_e32 v32, v27, v27
	v_fmac_f32_e32 v32, v28, v28
	v_fmac_f32_e32 v32, v29, v29
	v_fmac_f32_e32 v32, v30, v30
	v_fmac_f32_e32 v32, v31, v31
	v_fmac_f32_e32 v32, v0, v0
	v_fmac_f32_e32 v32, v1, v1
	v_fmac_f32_e32 v32, v2, v2
	v_fmac_f32_e32 v32, v3, v3
	v_fmac_f32_e32 v32, v4, v4
	v_fmac_f32_e32 v32, v5, v5
	v_fmac_f32_e32 v32, v6, v6
	v_fmac_f32_e32 v32, v7, v7
	v_fmac_f32_e32 v32, v8, v8
	v_fmac_f32_e32 v32, v9, v9
	v_fmac_f32_e32 v32, v10, v10
	v_fmac_f32_e32 v32, v11, v11
	v_fmac_f32_e32 v32, v12, v12
	v_fmac_f32_e32 v32, v13, v13
	v_cmp_lt_i32_e32 vcc, v199, v198
	v_fmac_f32_e32 v32, v14, v14
	v_fmac_f32_e32 v32, v15, v15
	v_cndmask_b32_e32 v33, v145, v199, vcc
	v_lshlrev_b32_e32 v33, 2, v33
	ds_bpermute_b32 v33, v33, v32
	v_cmp_eq_u32_e32 vcc, 0, v136
	s_and_saveexec_b64 s[0:1], vcc
	v_readlane_b32 s52, v250, 46
	s_cbranch_execz .LBB0_733
	s_waitcnt lgkmcnt(0)
	v_add_f32_e32 v32, v32, v33
	v_lshlrev_b32_e32 v33, 2, v135
	v_lshlrev_b32_e32 v34, 2, v109
	v_add3_u32 v33, s52, v33, v34
	ds_write_b32 v33, v32 offset:34816
	s_branch .LBB0_733

; __global__ void __launch_bounds__(512, 2) fwd_megakernel(Params P) {
	.amdhsa_kernel _Z14fwd_megakernel6Params
		.amdhsa_group_segment_fixed_size 0
		.amdhsa_private_segment_fixed_size 0
		.amdhsa_kernarg_size 656
		.amdhsa_user_sgpr_count 2
		.amdhsa_user_sgpr_dispatch_ptr 0
		.amdhsa_user_sgpr_queue_ptr 0
		.amdhsa_user_sgpr_kernarg_segment_ptr 1
		.amdhsa_user_sgpr_dispatch_id 0
		.amdhsa_user_sgpr_kernarg_preload_length 0
		.amdhsa_user_sgpr_kernarg_preload_offset 0
		.amdhsa_user_sgpr_private_segment_size 0
		.amdhsa_uses_dynamic_stack 0
		.amdhsa_enable_private_segment 0
		.amdhsa_system_sgpr_workgroup_id_x 1
		.amdhsa_system_sgpr_workgroup_id_y 0
		.amdhsa_system_sgpr_workgroup_id_z 0
		.amdhsa_system_sgpr_workgroup_info 0
		.amdhsa_system_vgpr_workitem_id 2
		.amdhsa_next_free_vgpr 256
		.amdhsa_next_free_sgpr 98
		.amdhsa_accum_offset 256
		.amdhsa_reserve_vcc 1
		.amdhsa_float_round_mode_32 0
		.amdhsa_float_round_mode_16_64 0
		.amdhsa_float_denorm_mode_32 3
		.amdhsa_float_denorm_mode_16_64 3
		.amdhsa_dx10_clamp 1
		.amdhsa_ieee_mode 1
		.amdhsa_fp16_overflow 0
		.amdhsa_tg_split 0
		.amdhsa_exception_fp_ieee_invalid_op 0
		.amdhsa_exception_fp_denorm_src 0
		.amdhsa_exception_fp_ieee_div_zero 0
		.amdhsa_exception_fp_ieee_overflow 0
		.amdhsa_exception_fp_ieee_underflow 0
		.amdhsa_exception_fp_ieee_inexact 0
		.amdhsa_exception_int_div_zero 0
	.end_amdhsa_kernel

; __global__ void __launch_bounds__(512, 2) fwd_megakernel(Params P) {
.Lfunc_end0:
	.size	_Z14fwd_megakernel6Params, .Lfunc_end0-_Z14fwd_megakernel6Params
	.set _Z14fwd_megakernel6Params.num_vgpr, 256
	.set _Z14fwd_megakernel6Params.num_agpr, 0
	.set _Z14fwd_megakernel6Params.numbered_sgpr, 98
	.set _Z14fwd_megakernel6Params.num_named_barrier, 0
	.set _Z14fwd_megakernel6Params.private_seg_size, 0
	.set _Z14fwd_megakernel6Params.uses_vcc, 1
	.set _Z14fwd_megakernel6Params.uses_flat_scratch, 0
	.set _Z14fwd_megakernel6Params.has_dyn_sized_stack, 0
	.set _Z14fwd_megakernel6Params.has_recursion, 0
	.set _Z14fwd_megakernel6Params.has_indirect_call, 0

; __global__ void __launch_bounds__(512, 2) fwd_megakernel(Params P) {
amdhsa.kernels:
  - .agpr_count:     0
    .args:
      - .offset:         0
        .size:           400
        .value_kind:     by_value
      - .offset:         400
        .size:           4
        .value_kind:     hidden_block_count_x
      - .offset:         404
        .size:           4
        .value_kind:     hidden_block_count_y
      - .offset:         408
        .size:           4
        .value_kind:     hidden_block_count_z
      - .offset:         412
        .size:           2
        .value_kind:     hidden_group_size_x
      - .offset:         414
        .size:           2
        .value_kind:     hidden_group_size_y
      - .offset:         416
        .size:           2
        .value_kind:     hidden_group_size_z
      - .offset:         418
        .size:           2
        .value_kind:     hidden_remainder_x
      - .offset:         420
        .size:           2
        .value_kind:     hidden_remainder_y
      - .offset:         422
        .size:           2
        .value_kind:     hidden_remainder_z
      - .offset:         440
        .size:           8
        .value_kind:     hidden_global_offset_x
      - .offset:         448
        .size:           8
        .value_kind:     hidden_global_offset_y
      - .offset:         456
        .size:           8
        .value_kind:     hidden_global_offset_z
      - .offset:         464
        .size:           2
        .value_kind:     hidden_grid_dims
      - .offset:         488
        .size:           8
        .value_kind:     hidden_multigrid_sync_arg
      - .offset:         520
        .size:           4
        .value_kind:     hidden_dynamic_lds_size
    .group_segment_fixed_size: 0
    .kernarg_segment_align: 8
    .kernarg_segment_size: 656
    .language:       OpenCL C
    .language_version:
      - 2
      - 0
    .max_flat_workgroup_size: 512
    .name:           _Z14fwd_megakernel6Params
    .private_segment_fixed_size: 0
    .sgpr_count:     104
    .sgpr_spill_count: 292
    .symbol:         _Z14fwd_megakernel6Params.kd
    .uniform_work_group_size: 1
    .uses_dynamic_stack: false
    .vgpr_count:     256
    .vgpr_spill_count: 0
    .wavefront_size: 64
